# grid barrier: the two spin loops keep up to 4 polls of the release word in flight instead of one round trip per poll
# speedup vs baseline: 1.0225x; 1.0012x over previous
; __device__ __forceinline__ unsigned xb_ld(unsigned* p)              { return __hip_atomic_load(p, __ATOMIC_RELAXED, __HIP_MEMORY_SCOPE_AGENT); }
; __device__ __forceinline__ unsigned xb_add(unsigned* p, unsigned v) { return __hip_atomic_fetch_add(p, v, __ATOMIC_RELAXED, __HIP_MEMORY_SCOPE_AGENT); }
; #define XB_SPIN(cond, bar) do { unsigned _sp = 0; while (cond) { __builtin_amdgcn_s_sleep(1); \
;     if ((++_sp & 255u) == 0u) { if (xb_ld(&(bar)[XB_TMO])) break; if (_sp > XB_SPIN_CAP) { atomicAdd(&(bar)[XB_TMO], 1u); break; } } } } while (0)
; __device__ __forceinline__ void xcd_barrier(const XcdBarrier& b) {
;     ...
;         const unsigned old = xb_add(&bar[XB_XSUB(b.x)], 1u);
;         const unsigned gen = old / nloc;
;         if (old + 1u == (gen + 1u) * nloc) {
;             __builtin_amdgcn_fence(__ATOMIC_RELEASE, "agent");
;             asm volatile("s_waitcnt vmcnt(0)" ::: "memory");
;             const unsigned og = xb_add(&bar[XB_TOP], 1u);
;             const unsigned tg = og / nx;
;             if (og + 1u == (tg + 1u) * nx) xb_add(&bar[XB_TOPGEN], 1u);
;             else XB_SPIN(xb_ld(&bar[XB_TOPGEN]) == tg, bar);
;             __builtin_amdgcn_fence(__ATOMIC_ACQUIRE, "agent");
;             xb_add(&bar[XB_XGEN(b.x)], 1u);
;             asm volatile("s_waitcnt vmcnt(0)" ::: "memory");
;         } else {
;             XB_SPIN(xb_ld(&bar[XB_XGEN(b.x)]) == gen, bar);
.LBB0_55:
	s_or_b64 exec, exec, s[8:9]
	v_cvt_f32_u32_e32 v4, v2
	s_waitcnt vmcnt(0)
	v_readfirstlane_b32 s6, v3
	v_sub_u32_e32 v3, 0, v2
	v_rcp_iflag_f32_e32 v4, v4
	v_add_u32_e32 v5, s6, v1
	v_mul_f32_e32 v4, 0x4f7ffffe, v4
	v_cvt_u32_f32_e32 v4, v4
	v_mul_lo_u32 v1, v3, v4
	v_mul_hi_u32 v1, v4, v1
	v_add_u32_e32 v1, v4, v1
	v_mul_hi_u32 v1, v5, v1
	v_mul_lo_u32 v3, v1, v2
	v_sub_u32_e32 v3, v5, v3
	v_add_u32_e32 v4, 1, v1
	v_cmp_ge_u32_e32 vcc, v3, v2
	s_nop 1
	v_cndmask_b32_e32 v1, v1, v4, vcc
	v_sub_u32_e32 v4, v3, v2
	v_cndmask_b32_e32 v3, v3, v4, vcc
	v_add_u32_e32 v4, 1, v1
	v_cmp_ge_u32_e32 vcc, v3, v2
	v_add_u32_e32 v3, 1, v5
	s_nop 0
	v_cndmask_b32_e32 v1, v1, v4, vcc
	v_mul_lo_u32 v4, v2, v1
	v_add_u32_e32 v2, v4, v2
	v_cmp_ne_u32_e32 vcc, v3, v2
	s_and_saveexec_b64 s[6:7], vcc
	s_xor_b64 s[6:7], exec, s[6:7]
	s_cbranch_execz .LBB0_69
	s_waitcnt lgkmcnt(0)
	global_load_dword v0, v252, s[4:5] offset:1024 sc1
	s_add_u32 s12, s4, 0x2400
	s_addc_u32 s13, s5, 0
	s_waitcnt vmcnt(0)
	v_cmp_eq_u32_e32 vcc, v0, v1
	s_and_saveexec_b64 s[8:9], vcc
	s_cbranch_execz .LBB0_68
	s_add_u32 s10, s2, 0x14880200
	s_addc_u32 s11, s3, 0
	s_mov_b32 s24, 1
	v_mov_b32_e32 v20, v1
	s_mov_b64 s[14:15], 0
	s_branch .LBB0_59

; __device__ __forceinline__ unsigned xb_ld(unsigned* p)              { return __hip_atomic_load(p, __ATOMIC_RELAXED, __HIP_MEMORY_SCOPE_AGENT); }
; #define XB_SPIN(cond, bar) do { unsigned _sp = 0; while (cond) { __builtin_amdgcn_s_sleep(1); \
;     if ((++_sp & 255u) == 0u) { if (xb_ld(&(bar)[XB_TMO])) break; if (_sp > XB_SPIN_CAP) { atomicAdd(&(bar)[XB_TMO], 1u); break; } } } } while (0)
; __device__ __forceinline__ void xcd_barrier(const XcdBarrier& b) {
;     ...
;             XB_SPIN(xb_ld(&bar[XB_XGEN(b.x)]) == gen, bar);
.LBB0_61:
	global_load_dword v20, v153, s[12:13] sc1
	s_add_i32 s24, s24, 1
	s_mov_b64 s[20:21], -1
	s_waitcnt vmcnt(3)
	v_cmp_ne_u32_e32 vcc, v20, v1
	s_orn2_b64 s[18:19], vcc, exec
	s_branch .LBB0_58

; __device__ __forceinline__ unsigned xb_ld(unsigned* p)              { return __hip_atomic_load(p, __ATOMIC_RELAXED, __HIP_MEMORY_SCOPE_AGENT); }
; __device__ __forceinline__ unsigned xb_add(unsigned* p, unsigned v) { return __hip_atomic_fetch_add(p, v, __ATOMIC_RELAXED, __HIP_MEMORY_SCOPE_AGENT); }
; #define XB_SPIN(cond, bar) do { unsigned _sp = 0; while (cond) { __builtin_amdgcn_s_sleep(1); \
;     if ((++_sp & 255u) == 0u) { if (xb_ld(&(bar)[XB_TMO])) break; if (_sp > XB_SPIN_CAP) { atomicAdd(&(bar)[XB_TMO], 1u); break; } } } } while (0)
; __device__ __forceinline__ void xcd_barrier(const XcdBarrier& b) {
;     ...
;             const unsigned og = xb_add(&bar[XB_TOP], 1u);
;             const unsigned tg = og / nx;
;             if (og + 1u == (tg + 1u) * nx) xb_add(&bar[XB_TOPGEN], 1u);
;             else XB_SPIN(xb_ld(&bar[XB_TOPGEN]) == tg, bar);
.LBB0_72:
	s_or_b64 exec, exec, s[8:9]
	v_cvt_f32_u32_e32 v3, v0
	s_waitcnt vmcnt(0)
	v_readfirstlane_b32 s6, v2
	s_mov_b64 s[10:11], -1
	v_rcp_iflag_f32_e32 v3, v3
	v_add_u32_e32 v1, s6, v1
	v_add_u32_e32 v4, 1, v1
	s_add_u32 s6, s2, 0x14883500
	v_mul_f32_e32 v2, 0x4f7ffffe, v3
	v_cvt_u32_f32_e32 v2, v2
	v_sub_u32_e32 v3, 0, v0
	s_addc_u32 s7, s3, 0
	v_mul_lo_u32 v3, v3, v2
	v_mul_hi_u32 v3, v2, v3
	v_add_u32_e32 v2, v2, v3
	v_mul_hi_u32 v2, v1, v2
	v_mul_lo_u32 v3, v2, v0
	v_sub_u32_e32 v1, v1, v3
	v_add_u32_e32 v5, 1, v2
	v_cmp_ge_u32_e32 vcc, v1, v0
	v_sub_u32_e32 v3, v1, v0
	s_nop 0
	v_cndmask_b32_e32 v2, v2, v5, vcc
	v_cndmask_b32_e32 v1, v1, v3, vcc
	v_add_u32_e32 v3, 1, v2
	v_cmp_ge_u32_e32 vcc, v1, v0
	s_nop 1
	v_cndmask_b32_e32 v2, v2, v3, vcc
	v_mul_lo_u32 v1, v0, v2
	v_add_u32_e32 v0, v1, v0
	v_cmp_ne_u32_e32 vcc, v4, v0
	v_mov_b64_e32 v[0:1], s[6:7]
	s_and_saveexec_b64 s[8:9], vcc
	s_cbranch_execz .LBB0_84
	global_load_dword v0, v153, s[6:7] sc1
	s_mov_b64 s[14:15], 0
	s_waitcnt vmcnt(0)
	v_cmp_eq_u32_e32 vcc, v0, v2
	s_and_saveexec_b64 s[12:13], vcc
	s_cbranch_execz .LBB0_83
	s_add_u32 s10, s2, 0x14880200
	s_addc_u32 s11, s3, 0
	s_mov_b32 s22, 1
	v_mov_b32_e32 v21, v2
	s_mov_b64 s[2:3], 0
	s_branch .LBB0_76

; __device__ __forceinline__ unsigned xb_ld(unsigned* p)              { return __hip_atomic_load(p, __ATOMIC_RELAXED, __HIP_MEMORY_SCOPE_AGENT); }
; #define XB_SPIN(cond, bar) do { unsigned _sp = 0; while (cond) { __builtin_amdgcn_s_sleep(1); \
;     if ((++_sp & 255u) == 0u) { if (xb_ld(&(bar)[XB_TMO])) break; if (_sp > XB_SPIN_CAP) { atomicAdd(&(bar)[XB_TMO], 1u); break; } } } } while (0)
; __device__ __forceinline__ void xcd_barrier(const XcdBarrier& b) {
;     ...
;             else XB_SPIN(xb_ld(&bar[XB_TOPGEN]) == tg, bar);
.LBB0_78:
	global_load_dword v21, v153, s[6:7] sc1
	s_add_i32 s22, s22, 1
	s_mov_b64 s[18:19], -1
	s_waitcnt vmcnt(3)
	v_cmp_ne_u32_e32 vcc, v21, v2
	s_orn2_b64 s[16:17], vcc, exec
	s_branch .LBB0_75

; template <class Epi, class Sched, bool ALIGN_EPI = false, bool SP2 = false>
; __device__ __forceinline__ void gemm_phase(PG8_LAS unsigned char* lds, const Gemm g, const Sched& S, const Epi& E) {
;     ...
;         if (!has_next) break;
; #pragma unroll
;         for (int a = 0; a < 2; ++a)
; #pragma unroll
;             for (int b = 0; b < 2; ++b)
; #pragma unroll
;                 for (int m = 0; m < 4; ++m)
; #pragma unroll
;                     for (int n = 0; n < 2; ++n) acc[a][b][m][n] = (f32x4){0.f, 0.f, 0.f, 0.f};
;         cur = nxt; cA = nA; cB = nB; ++ui;
.LBB0_115:
	v_mov_b32_e32 v135, 0
	s_andn2_b64 vcc, exec, s[18:19]
	v_mov_b32_e32 v134, 0
	v_mov_b32_e32 v137, 0
	v_mov_b32_e32 v136, 0
	v_mov_b32_e32 v127, 0
	v_mov_b32_e32 v126, 0
	v_mov_b32_e32 v125, 0
	v_mov_b32_e32 v124, 0
	v_mov_b32_e32 v119, 0
	v_mov_b32_e32 v118, 0
	v_mov_b32_e32 v117, 0
	v_mov_b32_e32 v116, 0
	v_mov_b32_e32 v111, 0
	v_mov_b32_e32 v110, 0
	v_mov_b32_e32 v109, 0
	v_mov_b32_e32 v108, 0
	v_mov_b32_e32 v103, 0
	v_mov_b32_e32 v102, 0
	v_mov_b32_e32 v101, 0
	v_mov_b32_e32 v100, 0
	v_mov_b32_e32 v95, 0
	v_mov_b32_e32 v94, 0
	v_mov_b32_e32 v93, 0
	v_mov_b32_e32 v92, 0
	v_mov_b32_e32 v87, 0
	v_mov_b32_e32 v86, 0
	v_mov_b32_e32 v85, 0
	v_mov_b32_e32 v84, 0
	v_mov_b32_e32 v75, 0
	v_mov_b32_e32 v74, 0
	v_mov_b32_e32 v73, 0
	v_mov_b32_e32 v72, 0
	v_mov_b32_e32 v145, 0
	v_mov_b32_e32 v144, 0
	v_mov_b32_e32 v143, 0
	v_mov_b32_e32 v142, 0
	v_mov_b32_e32 v141, 0
	v_mov_b32_e32 v140, 0
	v_mov_b32_e32 v139, 0
	v_mov_b32_e32 v138, 0
	v_mov_b32_e32 v123, 0
	v_mov_b32_e32 v122, 0
	v_mov_b32_e32 v121, 0
	v_mov_b32_e32 v120, 0
	v_mov_b32_e32 v115, 0
	v_mov_b32_e32 v114, 0
	v_mov_b32_e32 v113, 0
	v_mov_b32_e32 v112, 0
	v_mov_b32_e32 v107, 0
	v_mov_b32_e32 v106, 0
	v_mov_b32_e32 v105, 0
	v_mov_b32_e32 v104, 0
	v_mov_b32_e32 v99, 0
	v_mov_b32_e32 v98, 0
	v_mov_b32_e32 v97, 0
	v_mov_b32_e32 v96, 0
	v_mov_b32_e32 v91, 0
	v_mov_b32_e32 v90, 0
	v_mov_b32_e32 v89, 0
	v_mov_b32_e32 v88, 0
	v_mov_b32_e32 v83, 0
	v_mov_b32_e32 v82, 0
	v_mov_b32_e32 v81, 0
	v_mov_b32_e32 v80, 0
	v_mov_b32_e32 v67, 0
	v_mov_b32_e32 v66, 0
	v_mov_b32_e32 v65, 0
	v_mov_b32_e32 v64, 0
	v_mov_b32_e32 v63, 0
	v_mov_b32_e32 v62, 0
	v_mov_b32_e32 v61, 0
	v_mov_b32_e32 v60, 0
	v_mov_b32_e32 v55, 0
	v_mov_b32_e32 v54, 0
	v_mov_b32_e32 v53, 0
	v_mov_b32_e32 v52, 0
	v_mov_b32_e32 v47, 0
	v_mov_b32_e32 v46, 0
	v_mov_b32_e32 v45, 0
	v_mov_b32_e32 v44, 0
	v_mov_b32_e32 v31, 0
	v_mov_b32_e32 v30, 0
	v_mov_b32_e32 v29, 0
	v_mov_b32_e32 v28, 0
	v_mov_b32_e32 v23, 0
	v_mov_b32_e32 v22, 0
	v_mov_b32_e32 v21, 0
	v_mov_b32_e32 v20, 0
	v_mov_b32_e32 v15, 0
	v_mov_b32_e32 v14, 0
	v_mov_b32_e32 v13, 0
	v_mov_b32_e32 v12, 0
	v_mov_b32_e32 v11, 0
	v_mov_b32_e32 v10, 0
	v_mov_b32_e32 v9, 0
	v_mov_b32_e32 v8, 0
	v_mov_b32_e32 v79, 0
	v_mov_b32_e32 v78, 0
	v_mov_b32_e32 v77, 0
	v_mov_b32_e32 v76, 0
	v_mov_b32_e32 v71, 0
	v_mov_b32_e32 v70, 0
	v_mov_b32_e32 v69, 0
	v_mov_b32_e32 v68, 0
	v_mov_b32_e32 v59, 0
	v_mov_b32_e32 v58, 0
	v_mov_b32_e32 v57, 0
	v_mov_b32_e32 v56, 0
	v_mov_b32_e32 v51, 0
	v_mov_b32_e32 v50, 0
	v_mov_b32_e32 v49, 0
	v_mov_b32_e32 v48, 0
	v_mov_b32_e32 v39, 0
	v_mov_b32_e32 v38, 0
	v_mov_b32_e32 v37, 0
	v_mov_b32_e32 v36, 0
	v_mov_b32_e32 v35, 0
	v_mov_b32_e32 v34, 0
	v_mov_b32_e32 v33, 0
	v_mov_b32_e32 v32, 0
	v_mov_b32_e32 v7, 0
	v_mov_b32_e32 v6, 0
	v_mov_b32_e32 v5, 0
	v_mov_b32_e32 v4, 0
	v_mov_b32_e32 v3, 0
	v_mov_b32_e32 v2, 0
	v_mov_b32_e32 v1, 0
	v_mov_b32_e32 v0, 0
	s_cbranch_vccnz .LBB0_119
	s_add_u32 s0, s0, 0x80
	s_addc_u32 s1, s1, 0
	s_add_u32 s34, s2, 0x100
	v_mov_b32_e32 v0, 0
	s_addc_u32 s35, s3, 0
	s_mov_b32 s2, 0
	v_mov_b32_e32 v1, v0
	v_mov_b32_e32 v2, v0
	v_mov_b32_e32 v3, v0
	v_mov_b32_e32 v4, v0
	v_mov_b32_e32 v5, v0
	v_mov_b32_e32 v6, v0
	v_mov_b32_e32 v7, v0
	v_mov_b32_e32 v8, v0
	v_mov_b32_e32 v9, v0
	v_mov_b32_e32 v10, v0
	v_mov_b32_e32 v11, v0
	v_mov_b32_e32 v12, v0
	v_mov_b32_e32 v13, v0
	v_mov_b32_e32 v14, v0
	v_mov_b32_e32 v15, v0
	v_mov_b32_e32 v20, v0
	v_mov_b32_e32 v21, v0
	v_mov_b32_e32 v22, v0
	v_mov_b32_e32 v23, v0
	v_mov_b32_e32 v28, v0
	v_mov_b32_e32 v29, v0
	v_mov_b32_e32 v30, v0
	v_mov_b32_e32 v31, v0
	v_mov_b32_e32 v36, v0
	v_mov_b32_e32 v37, v0
	v_mov_b32_e32 v38, v0
	v_mov_b32_e32 v39, v0
	v_mov_b32_e32 v44, v0
	v_mov_b32_e32 v45, v0
	v_mov_b32_e32 v46, v0
	v_mov_b32_e32 v47, v0
	v_mov_b32_e32 v16, v0
	v_mov_b32_e32 v17, v0
	v_mov_b32_e32 v18, v0
	v_mov_b32_e32 v19, v0
	v_mov_b32_e32 v24, v0
	v_mov_b32_e32 v25, v0
	v_mov_b32_e32 v26, v0
	v_mov_b32_e32 v27, v0
	v_mov_b32_e32 v32, v0
	v_mov_b32_e32 v33, v0
	v_mov_b32_e32 v34, v0
	v_mov_b32_e32 v35, v0
	v_mov_b32_e32 v40, v0
	v_mov_b32_e32 v41, v0
	v_mov_b32_e32 v42, v0
	v_mov_b32_e32 v43, v0
	v_mov_b32_e32 v48, v0
	v_mov_b32_e32 v49, v0
	v_mov_b32_e32 v50, v0
	v_mov_b32_e32 v51, v0
	v_mov_b32_e32 v52, v0
	v_mov_b32_e32 v53, v0
	v_mov_b32_e32 v54, v0
	v_mov_b32_e32 v55, v0
	v_mov_b32_e32 v56, v0
	v_mov_b32_e32 v57, v0
	v_mov_b32_e32 v58, v0
	v_mov_b32_e32 v59, v0
	v_mov_b32_e32 v60, v0
	v_mov_b32_e32 v61, v0
	v_mov_b32_e32 v62, v0
	v_mov_b32_e32 v63, v0
	v_mov_b32_e32 v64, v0
	v_mov_b32_e32 v65, v0
	v_mov_b32_e32 v66, v0
	v_mov_b32_e32 v67, v0
	v_mov_b32_e32 v68, v0
	v_mov_b32_e32 v69, v0
	v_mov_b32_e32 v70, v0
	v_mov_b32_e32 v71, v0
	v_mov_b32_e32 v72, v0
	v_mov_b32_e32 v73, v0
	v_mov_b32_e32 v74, v0
	v_mov_b32_e32 v75, v0
	v_mov_b32_e32 v76, v0
	v_mov_b32_e32 v77, v0
	v_mov_b32_e32 v78, v0
	v_mov_b32_e32 v79, v0
	v_mov_b32_e32 v84, v0
	v_mov_b32_e32 v85, v0
	v_mov_b32_e32 v86, v0
	v_mov_b32_e32 v87, v0
	v_mov_b32_e32 v92, v0
	v_mov_b32_e32 v93, v0
	v_mov_b32_e32 v94, v0
	v_mov_b32_e32 v95, v0
	v_mov_b32_e32 v100, v0
	v_mov_b32_e32 v101, v0
	v_mov_b32_e32 v102, v0
	v_mov_b32_e32 v103, v0
	v_mov_b32_e32 v108, v0
	v_mov_b32_e32 v109, v0
	v_mov_b32_e32 v110, v0
	v_mov_b32_e32 v111, v0
	v_mov_b32_e32 v80, v0
	v_mov_b32_e32 v81, v0
	v_mov_b32_e32 v82, v0
	v_mov_b32_e32 v83, v0
	v_mov_b32_e32 v88, v0
	v_mov_b32_e32 v89, v0
	v_mov_b32_e32 v90, v0
	v_mov_b32_e32 v91, v0
	v_mov_b32_e32 v96, v0
	v_mov_b32_e32 v97, v0
	v_mov_b32_e32 v98, v0
	v_mov_b32_e32 v99, v0
	v_mov_b32_e32 v104, v0
	v_mov_b32_e32 v105, v0
	v_mov_b32_e32 v106, v0
	v_mov_b32_e32 v107, v0
	v_mov_b32_e32 v112, v0
	v_mov_b32_e32 v113, v0
	v_mov_b32_e32 v114, v0
	v_mov_b32_e32 v115, v0
	v_mov_b32_e32 v116, v0
	v_mov_b32_e32 v117, v0
	v_mov_b32_e32 v118, v0
	v_mov_b32_e32 v119, v0
	v_mov_b32_e32 v120, v0
	v_mov_b32_e32 v121, v0
	v_mov_b32_e32 v122, v0
	v_mov_b32_e32 v123, v0
	v_mov_b32_e32 v124, v0
	v_mov_b32_e32 v125, v0
	v_mov_b32_e32 v126, v0
	v_mov_b32_e32 v127, v0
	v_readfirstlane_b32 s101, v211
	s_cmp_ge_u32 s101, 0x100
	s_cbranch_scc0 .Lprio_skip12
	s_setprio 1

; template <class Epi, class Sched, bool ALIGN_EPI = false, bool SP2 = false>
; __device__ __forceinline__ void gemm_phase(PG8_LAS unsigned char* lds, const Gemm g, const Sched& S, const Epi& E) {
;     ...
;         if (!has_next) break;
; #pragma unroll
;         for (int a = 0; a < 2; ++a)
; #pragma unroll
;             for (int b = 0; b < 2; ++b)
; #pragma unroll
;                 for (int m = 0; m < 4; ++m)
; #pragma unroll
;                     for (int n = 0; n < 2; ++n) acc[a][b][m][n] = (f32x4){0.f, 0.f, 0.f, 0.f};
;         cur = nxt; cA = nA; cB = nB; ++ui;
.LBB0_156:
	v_mov_b32_e32 v127, 0
	s_andn2_b64 vcc, exec, s[18:19]
	v_mov_b32_e32 v126, v127
	v_mov_b32_e32 v125, v127
	v_mov_b32_e32 v124, v127
	v_mov_b32_e32 v123, v127
	v_mov_b32_e32 v122, v127
	v_mov_b32_e32 v121, v127
	v_mov_b32_e32 v120, v127
	v_mov_b32_e32 v111, v127
	v_mov_b32_e32 v110, v127
	v_mov_b32_e32 v109, v127
	v_mov_b32_e32 v108, v127
	v_mov_b32_e32 v107, v127
	v_mov_b32_e32 v106, v127
	v_mov_b32_e32 v105, v127
	v_mov_b32_e32 v104, v127
	v_mov_b32_e32 v95, v127
	v_mov_b32_e32 v94, v127
	v_mov_b32_e32 v93, v127
	v_mov_b32_e32 v92, v127
	v_mov_b32_e32 v91, v127
	v_mov_b32_e32 v90, v127
	v_mov_b32_e32 v89, v127
	v_mov_b32_e32 v88, v127
	v_mov_b32_e32 v79, v127
	v_mov_b32_e32 v78, v127
	v_mov_b32_e32 v77, v127
	v_mov_b32_e32 v76, v127
	v_mov_b32_e32 v75, v127
	v_mov_b32_e32 v74, v127
	v_mov_b32_e32 v73, v127
	v_mov_b32_e32 v72, v127
	v_mov_b32_e32 v119, v127
	v_mov_b32_e32 v118, v127
	v_mov_b32_e32 v117, v127
	v_mov_b32_e32 v116, v127
	v_mov_b32_e32 v115, v127
	v_mov_b32_e32 v114, v127
	v_mov_b32_e32 v113, v127
	v_mov_b32_e32 v112, v127
	v_mov_b32_e32 v103, v127
	v_mov_b32_e32 v102, v127
	v_mov_b32_e32 v101, v127
	v_mov_b32_e32 v100, v127
	v_mov_b32_e32 v99, v127
	v_mov_b32_e32 v98, v127
	v_mov_b32_e32 v97, v127
	v_mov_b32_e32 v96, v127
	v_mov_b32_e32 v87, v127
	v_mov_b32_e32 v86, v127
	v_mov_b32_e32 v85, v127
	v_mov_b32_e32 v84, v127
	v_mov_b32_e32 v83, v127
	v_mov_b32_e32 v82, v127
	v_mov_b32_e32 v81, v127
	v_mov_b32_e32 v80, v127
	v_mov_b32_e32 v71, v127
	v_mov_b32_e32 v70, v127
	v_mov_b32_e32 v69, v127
	v_mov_b32_e32 v68, v127
	v_mov_b32_e32 v67, v127
	v_mov_b32_e32 v66, v127
	v_mov_b32_e32 v65, v127
	v_mov_b32_e32 v64, v127
	v_mov_b32_e32 v63, v127
	v_mov_b32_e32 v62, v127
	v_mov_b32_e32 v61, v127
	v_mov_b32_e32 v60, v127
	v_mov_b32_e32 v59, v127
	v_mov_b32_e32 v58, v127
	v_mov_b32_e32 v57, v127
	v_mov_b32_e32 v56, v127
	v_mov_b32_e32 v47, v127
	v_mov_b32_e32 v46, v127
	v_mov_b32_e32 v45, v127
	v_mov_b32_e32 v44, v127
	v_mov_b32_e32 v43, v127
	v_mov_b32_e32 v42, v127
	v_mov_b32_e32 v41, v127
	v_mov_b32_e32 v40, v127
	v_mov_b32_e32 v31, v127
	v_mov_b32_e32 v30, v127
	v_mov_b32_e32 v29, v127
	v_mov_b32_e32 v28, v127
	v_mov_b32_e32 v27, v127
	v_mov_b32_e32 v26, v127
	v_mov_b32_e32 v25, v127
	v_mov_b32_e32 v24, v127
	v_mov_b32_e32 v15, v127
	v_mov_b32_e32 v14, v127
	v_mov_b32_e32 v13, v127
	v_mov_b32_e32 v12, v127
	v_mov_b32_e32 v11, v127
	v_mov_b32_e32 v10, v127
	v_mov_b32_e32 v9, v127
	v_mov_b32_e32 v8, v127
	v_mov_b32_e32 v55, v127
	v_mov_b32_e32 v54, v127
	v_mov_b32_e32 v53, v127
	v_mov_b32_e32 v52, v127
	v_mov_b32_e32 v51, v127
	v_mov_b32_e32 v50, v127
	v_mov_b32_e32 v49, v127
	v_mov_b32_e32 v48, v127
	v_mov_b32_e32 v39, v127
	v_mov_b32_e32 v38, v127
	v_mov_b32_e32 v37, v127
	v_mov_b32_e32 v36, v127
	v_mov_b32_e32 v35, v127
	v_mov_b32_e32 v34, v127
	v_mov_b32_e32 v33, v127
	v_mov_b32_e32 v32, v127
	v_mov_b32_e32 v23, v127
	v_mov_b32_e32 v22, v127
	v_mov_b32_e32 v21, v127
	v_mov_b32_e32 v20, v127
	v_mov_b32_e32 v19, v127
	v_mov_b32_e32 v18, v127
	v_mov_b32_e32 v17, v127
	v_mov_b32_e32 v16, v127
	v_mov_b32_e32 v7, v127
	v_mov_b32_e32 v6, v127
	v_mov_b32_e32 v5, v127
	v_mov_b32_e32 v4, v127
	v_mov_b32_e32 v3, v127
	v_mov_b32_e32 v2, v127
	v_mov_b32_e32 v1, v127
	v_mov_b32_e32 v0, v127
	s_cbranch_vccnz .LBB0_159
	s_add_u32 s0, s0, 0x80
	s_addc_u32 s1, s1, 0
	s_add_u32 s36, s2, 0x100
	v_mov_b32_e32 v0, 0
	s_addc_u32 s37, s3, 0
	s_mov_b32 s2, 0
	v_mov_b32_e32 v1, v0
	v_mov_b32_e32 v2, v0
	v_mov_b32_e32 v3, v0
	v_mov_b32_e32 v4, v0
	v_mov_b32_e32 v5, v0
	v_mov_b32_e32 v6, v0
	v_mov_b32_e32 v7, v0
	v_mov_b32_e32 v16, v0
	v_mov_b32_e32 v17, v0
	v_mov_b32_e32 v18, v0
	v_mov_b32_e32 v19, v0
	v_mov_b32_e32 v20, v0
	v_mov_b32_e32 v21, v0
	v_mov_b32_e32 v22, v0
	v_mov_b32_e32 v23, v0
	v_mov_b32_e32 v32, v0
	v_mov_b32_e32 v33, v0
	v_mov_b32_e32 v34, v0
	v_mov_b32_e32 v35, v0
	v_mov_b32_e32 v36, v0
	v_mov_b32_e32 v37, v0
	v_mov_b32_e32 v38, v0
	v_mov_b32_e32 v39, v0
	v_mov_b32_e32 v48, v0
	v_mov_b32_e32 v49, v0
	v_mov_b32_e32 v50, v0
	v_mov_b32_e32 v51, v0
	v_mov_b32_e32 v52, v0
	v_mov_b32_e32 v53, v0
	v_mov_b32_e32 v54, v0
	v_mov_b32_e32 v55, v0
	v_mov_b32_e32 v8, v0
	v_mov_b32_e32 v9, v0
	v_mov_b32_e32 v10, v0
	v_mov_b32_e32 v11, v0
	v_mov_b32_e32 v12, v0
	v_mov_b32_e32 v13, v0
	v_mov_b32_e32 v14, v0
	v_mov_b32_e32 v15, v0
	v_mov_b32_e32 v24, v0
	v_mov_b32_e32 v25, v0
	v_mov_b32_e32 v26, v0
	v_mov_b32_e32 v27, v0
	v_mov_b32_e32 v28, v0
	v_mov_b32_e32 v29, v0
	v_mov_b32_e32 v30, v0
	v_mov_b32_e32 v31, v0
	v_mov_b32_e32 v40, v0
	v_mov_b32_e32 v41, v0
	v_mov_b32_e32 v42, v0
	v_mov_b32_e32 v43, v0
	v_mov_b32_e32 v44, v0
	v_mov_b32_e32 v45, v0
	v_mov_b32_e32 v46, v0
	v_mov_b32_e32 v47, v0
	v_mov_b32_e32 v56, v0
	v_mov_b32_e32 v57, v0
	v_mov_b32_e32 v58, v0
	v_mov_b32_e32 v59, v0
	v_mov_b32_e32 v60, v0
	v_mov_b32_e32 v61, v0
	v_mov_b32_e32 v62, v0
	v_mov_b32_e32 v63, v0
	v_mov_b32_e32 v64, v0
	v_mov_b32_e32 v65, v0
	v_mov_b32_e32 v66, v0
	v_mov_b32_e32 v67, v0
	v_mov_b32_e32 v68, v0
	v_mov_b32_e32 v69, v0
	v_mov_b32_e32 v70, v0
	v_mov_b32_e32 v71, v0
	v_mov_b32_e32 v80, v0
	v_mov_b32_e32 v81, v0
	v_mov_b32_e32 v82, v0
	v_mov_b32_e32 v83, v0
	v_mov_b32_e32 v84, v0
	v_mov_b32_e32 v85, v0
	v_mov_b32_e32 v86, v0
	v_mov_b32_e32 v87, v0
	v_mov_b32_e32 v96, v0
	v_mov_b32_e32 v97, v0
	v_mov_b32_e32 v98, v0
	v_mov_b32_e32 v99, v0
	v_mov_b32_e32 v100, v0
	v_mov_b32_e32 v101, v0
	v_mov_b32_e32 v102, v0
	v_mov_b32_e32 v103, v0
	v_mov_b32_e32 v112, v0
	v_mov_b32_e32 v113, v0
	v_mov_b32_e32 v114, v0
	v_mov_b32_e32 v115, v0
	v_mov_b32_e32 v116, v0
	v_mov_b32_e32 v117, v0
	v_mov_b32_e32 v118, v0
	v_mov_b32_e32 v119, v0
	v_mov_b32_e32 v72, v0
	v_mov_b32_e32 v73, v0
	v_mov_b32_e32 v74, v0
	v_mov_b32_e32 v75, v0
	v_mov_b32_e32 v76, v0
	v_mov_b32_e32 v77, v0
	v_mov_b32_e32 v78, v0
	v_mov_b32_e32 v79, v0
	v_mov_b32_e32 v88, v0
	v_mov_b32_e32 v89, v0
	v_mov_b32_e32 v90, v0
	v_mov_b32_e32 v91, v0
	v_mov_b32_e32 v92, v0
	v_mov_b32_e32 v93, v0
	v_mov_b32_e32 v94, v0
	v_mov_b32_e32 v95, v0
	v_mov_b32_e32 v104, v0
	v_mov_b32_e32 v105, v0
	v_mov_b32_e32 v106, v0
	v_mov_b32_e32 v107, v0
	v_mov_b32_e32 v108, v0
	v_mov_b32_e32 v109, v0
	v_mov_b32_e32 v110, v0
	v_mov_b32_e32 v111, v0
	v_mov_b32_e32 v120, v0
	v_mov_b32_e32 v121, v0
	v_mov_b32_e32 v122, v0
	v_mov_b32_e32 v123, v0
	v_mov_b32_e32 v124, v0
	v_mov_b32_e32 v125, v0
	v_mov_b32_e32 v126, v0
	v_mov_b32_e32 v127, v0
	v_readfirstlane_b32 s101, v211
	s_cmp_ge_u32 s101, 0x100
	s_cbranch_scc0 .Lprio_skip11
	s_setprio 1

; template <class Epi, class Sched, bool ALIGN_EPI = false, bool SP2 = false>
; __device__ __forceinline__ void gemm_phase(PG8_LAS unsigned char* lds, const Gemm g, const Sched& S, const Epi& E) {
;     ...
;         if (!has_next) break;
; #pragma unroll
;         for (int a = 0; a < 2; ++a)
; #pragma unroll
;             for (int b = 0; b < 2; ++b)
; #pragma unroll
;                 for (int m = 0; m < 4; ++m)
; #pragma unroll
;                     for (int n = 0; n < 2; ++n) acc[a][b][m][n] = (f32x4){0.f, 0.f, 0.f, 0.f};
;         cur = nxt; cA = nA; cB = nB; ++ui;
.LBB0_192:
	v_mov_b32_e32 v123, 0
	s_andn2_b64 vcc, exec, s[18:19]
	v_mov_b32_e32 v122, v123
	v_mov_b32_e32 v121, v123
	v_mov_b32_e32 v120, v123
	v_mov_b32_e32 v127, v123
	v_mov_b32_e32 v126, v123
	v_mov_b32_e32 v125, v123
	v_mov_b32_e32 v124, v123
	v_mov_b32_e32 v111, v123
	v_mov_b32_e32 v110, v123
	v_mov_b32_e32 v109, v123
	v_mov_b32_e32 v108, v123
	v_mov_b32_e32 v107, v123
	v_mov_b32_e32 v106, v123
	v_mov_b32_e32 v105, v123
	v_mov_b32_e32 v104, v123
	v_mov_b32_e32 v95, v123
	v_mov_b32_e32 v94, v123
	v_mov_b32_e32 v93, v123
	v_mov_b32_e32 v92, v123
	v_mov_b32_e32 v91, v123
	v_mov_b32_e32 v90, v123
	v_mov_b32_e32 v89, v123
	v_mov_b32_e32 v88, v123
	v_mov_b32_e32 v79, v123
	v_mov_b32_e32 v78, v123
	v_mov_b32_e32 v77, v123
	v_mov_b32_e32 v76, v123
	v_mov_b32_e32 v75, v123
	v_mov_b32_e32 v74, v123
	v_mov_b32_e32 v73, v123
	v_mov_b32_e32 v72, v123
	v_mov_b32_e32 v119, v123
	v_mov_b32_e32 v118, v123
	v_mov_b32_e32 v117, v123
	v_mov_b32_e32 v116, v123
	v_mov_b32_e32 v115, v123
	v_mov_b32_e32 v114, v123
	v_mov_b32_e32 v113, v123
	v_mov_b32_e32 v112, v123
	v_mov_b32_e32 v103, v123
	v_mov_b32_e32 v102, v123
	v_mov_b32_e32 v101, v123
	v_mov_b32_e32 v100, v123
	v_mov_b32_e32 v99, v123
	v_mov_b32_e32 v98, v123
	v_mov_b32_e32 v97, v123
	v_mov_b32_e32 v96, v123
	v_mov_b32_e32 v87, v123
	v_mov_b32_e32 v86, v123
	v_mov_b32_e32 v85, v123
	v_mov_b32_e32 v84, v123
	v_mov_b32_e32 v83, v123
	v_mov_b32_e32 v82, v123
	v_mov_b32_e32 v81, v123
	v_mov_b32_e32 v80, v123
	v_mov_b32_e32 v71, v123
	v_mov_b32_e32 v70, v123
	v_mov_b32_e32 v69, v123
	v_mov_b32_e32 v68, v123
	v_mov_b32_e32 v67, v123
	v_mov_b32_e32 v66, v123
	v_mov_b32_e32 v65, v123
	v_mov_b32_e32 v64, v123
	v_mov_b32_e32 v63, v123
	v_mov_b32_e32 v62, v123
	v_mov_b32_e32 v61, v123
	v_mov_b32_e32 v60, v123
	v_mov_b32_e32 v59, v123
	v_mov_b32_e32 v58, v123
	v_mov_b32_e32 v57, v123
	v_mov_b32_e32 v56, v123
	v_mov_b32_e32 v47, v123
	v_mov_b32_e32 v46, v123
	v_mov_b32_e32 v45, v123
	v_mov_b32_e32 v44, v123
	v_mov_b32_e32 v43, v123
	v_mov_b32_e32 v42, v123
	v_mov_b32_e32 v41, v123
	v_mov_b32_e32 v40, v123
	v_mov_b32_e32 v31, v123
	v_mov_b32_e32 v30, v123
	v_mov_b32_e32 v29, v123
	v_mov_b32_e32 v28, v123
	v_mov_b32_e32 v27, v123
	v_mov_b32_e32 v26, v123
	v_mov_b32_e32 v25, v123
	v_mov_b32_e32 v24, v123
	v_mov_b32_e32 v15, v123
	v_mov_b32_e32 v14, v123
	v_mov_b32_e32 v13, v123
	v_mov_b32_e32 v12, v123
	v_mov_b32_e32 v11, v123
	v_mov_b32_e32 v10, v123
	v_mov_b32_e32 v9, v123
	v_mov_b32_e32 v8, v123
	v_mov_b32_e32 v55, v123
	v_mov_b32_e32 v54, v123
	v_mov_b32_e32 v53, v123
	v_mov_b32_e32 v52, v123
	v_mov_b32_e32 v51, v123
	v_mov_b32_e32 v50, v123
	v_mov_b32_e32 v49, v123
	v_mov_b32_e32 v48, v123
	v_mov_b32_e32 v39, v123
	v_mov_b32_e32 v38, v123
	v_mov_b32_e32 v37, v123
	v_mov_b32_e32 v36, v123
	v_mov_b32_e32 v35, v123
	v_mov_b32_e32 v34, v123
	v_mov_b32_e32 v33, v123
	v_mov_b32_e32 v32, v123
	v_mov_b32_e32 v23, v123
	v_mov_b32_e32 v22, v123
	v_mov_b32_e32 v21, v123
	v_mov_b32_e32 v20, v123
	v_mov_b32_e32 v19, v123
	v_mov_b32_e32 v18, v123
	v_mov_b32_e32 v17, v123
	v_mov_b32_e32 v16, v123
	v_mov_b32_e32 v7, v123
	v_mov_b32_e32 v6, v123
	v_mov_b32_e32 v5, v123
	v_mov_b32_e32 v4, v123
	v_mov_b32_e32 v3, v123
	v_mov_b32_e32 v2, v123
	v_mov_b32_e32 v1, v123
	v_mov_b32_e32 v0, v123
	s_cbranch_vccnz .LBB0_195
	s_add_u32 s6, s20, 0x80
	s_addc_u32 s7, s21, 0
	s_add_u32 s20, s8, 0x100
	v_mov_b32_e32 v0, 0
	s_addc_u32 s21, s9, 0
	s_mov_b32 s8, 0
	v_mov_b32_e32 v1, v0
	v_mov_b32_e32 v2, v0
	v_mov_b32_e32 v3, v0
	v_mov_b32_e32 v4, v0
	v_mov_b32_e32 v5, v0
	v_mov_b32_e32 v6, v0
	v_mov_b32_e32 v7, v0
	v_mov_b32_e32 v16, v0
	v_mov_b32_e32 v17, v0
	v_mov_b32_e32 v18, v0
	v_mov_b32_e32 v19, v0
	v_mov_b32_e32 v20, v0
	v_mov_b32_e32 v21, v0
	v_mov_b32_e32 v22, v0
	v_mov_b32_e32 v23, v0
	v_mov_b32_e32 v32, v0
	v_mov_b32_e32 v33, v0
	v_mov_b32_e32 v34, v0
	v_mov_b32_e32 v35, v0
	v_mov_b32_e32 v36, v0
	v_mov_b32_e32 v37, v0
	v_mov_b32_e32 v38, v0
	v_mov_b32_e32 v39, v0
	v_mov_b32_e32 v48, v0
	v_mov_b32_e32 v49, v0
	v_mov_b32_e32 v50, v0
	v_mov_b32_e32 v51, v0
	v_mov_b32_e32 v52, v0
	v_mov_b32_e32 v53, v0
	v_mov_b32_e32 v54, v0
	v_mov_b32_e32 v55, v0
	v_mov_b32_e32 v8, v0
	v_mov_b32_e32 v9, v0
	v_mov_b32_e32 v10, v0
	v_mov_b32_e32 v11, v0
	v_mov_b32_e32 v12, v0
	v_mov_b32_e32 v13, v0
	v_mov_b32_e32 v14, v0
	v_mov_b32_e32 v15, v0
	v_mov_b32_e32 v24, v0
	v_mov_b32_e32 v25, v0
	v_mov_b32_e32 v26, v0
	v_mov_b32_e32 v27, v0
	v_mov_b32_e32 v28, v0
	v_mov_b32_e32 v29, v0
	v_mov_b32_e32 v30, v0
	v_mov_b32_e32 v31, v0
	v_mov_b32_e32 v40, v0
	v_mov_b32_e32 v41, v0
	v_mov_b32_e32 v42, v0
	v_mov_b32_e32 v43, v0
	v_mov_b32_e32 v44, v0
	v_mov_b32_e32 v45, v0
	v_mov_b32_e32 v46, v0
	v_mov_b32_e32 v47, v0
	v_mov_b32_e32 v56, v0
	v_mov_b32_e32 v57, v0
	v_mov_b32_e32 v58, v0
	v_mov_b32_e32 v59, v0
	v_mov_b32_e32 v60, v0
	v_mov_b32_e32 v61, v0
	v_mov_b32_e32 v62, v0
	v_mov_b32_e32 v63, v0
	v_mov_b32_e32 v64, v0
	v_mov_b32_e32 v65, v0
	v_mov_b32_e32 v66, v0
	v_mov_b32_e32 v67, v0
	v_mov_b32_e32 v68, v0
	v_mov_b32_e32 v69, v0
	v_mov_b32_e32 v70, v0
	v_mov_b32_e32 v71, v0
	v_mov_b32_e32 v80, v0
	v_mov_b32_e32 v81, v0
	v_mov_b32_e32 v82, v0
	v_mov_b32_e32 v83, v0
	v_mov_b32_e32 v84, v0
	v_mov_b32_e32 v85, v0
	v_mov_b32_e32 v86, v0
	v_mov_b32_e32 v87, v0
	v_mov_b32_e32 v96, v0
	v_mov_b32_e32 v97, v0
	v_mov_b32_e32 v98, v0
	v_mov_b32_e32 v99, v0
	v_mov_b32_e32 v100, v0
	v_mov_b32_e32 v101, v0
	v_mov_b32_e32 v102, v0
	v_mov_b32_e32 v103, v0
	v_mov_b32_e32 v112, v0
	v_mov_b32_e32 v113, v0
	v_mov_b32_e32 v114, v0
	v_mov_b32_e32 v115, v0
	v_mov_b32_e32 v116, v0
	v_mov_b32_e32 v117, v0
	v_mov_b32_e32 v118, v0
	v_mov_b32_e32 v119, v0
	v_mov_b32_e32 v72, v0
	v_mov_b32_e32 v73, v0
	v_mov_b32_e32 v74, v0
	v_mov_b32_e32 v75, v0
	v_mov_b32_e32 v76, v0
	v_mov_b32_e32 v77, v0
	v_mov_b32_e32 v78, v0
	v_mov_b32_e32 v79, v0
	v_mov_b32_e32 v88, v0
	v_mov_b32_e32 v89, v0
	v_mov_b32_e32 v90, v0
	v_mov_b32_e32 v91, v0
	v_mov_b32_e32 v92, v0
	v_mov_b32_e32 v93, v0
	v_mov_b32_e32 v94, v0
	v_mov_b32_e32 v95, v0
	v_mov_b32_e32 v104, v0
	v_mov_b32_e32 v105, v0
	v_mov_b32_e32 v106, v0
	v_mov_b32_e32 v107, v0
	v_mov_b32_e32 v108, v0
	v_mov_b32_e32 v109, v0
	v_mov_b32_e32 v110, v0
	v_mov_b32_e32 v111, v0
	v_mov_b32_e32 v124, v0
	v_mov_b32_e32 v125, v0
	v_mov_b32_e32 v126, v0
	v_mov_b32_e32 v127, v0
	v_mov_b32_e32 v120, v0
	v_mov_b32_e32 v121, v0
	v_mov_b32_e32 v122, v0
	v_mov_b32_e32 v123, v0
	v_readfirstlane_b32 s101, v211
	s_cmp_ge_u32 s101, 0x100
	s_cbranch_scc0 .Lprio_skip10
	s_setprio 1

; template <class Epi, class Sched, bool ALIGN_EPI = false, bool SP2 = false>
; __device__ __forceinline__ void gemm_phase(PG8_LAS unsigned char* lds, const Gemm g, const Sched& S, const Epi& E) {
;     ...
;         if (!has_next) break;
; #pragma unroll
;         for (int a = 0; a < 2; ++a)
; #pragma unroll
;             for (int b = 0; b < 2; ++b)
; #pragma unroll
;                 for (int m = 0; m < 4; ++m)
; #pragma unroll
;                     for (int n = 0; n < 2; ++n) acc[a][b][m][n] = (f32x4){0.f, 0.f, 0.f, 0.f};
;         cur = nxt; cA = nA; cB = nB; ++ui;
.LBB0_361:
	v_mov_b32_e32 v127, 0
	s_andn2_b64 vcc, exec, s[46:47]
	v_mov_b32_e32 v126, v127
	v_mov_b32_e32 v125, v127
	v_mov_b32_e32 v124, v127
	v_mov_b32_e32 v123, v127
	v_mov_b32_e32 v122, v127
	v_mov_b32_e32 v121, v127
	v_mov_b32_e32 v120, v127
	v_mov_b32_e32 v119, v127
	v_mov_b32_e32 v118, v127
	v_mov_b32_e32 v117, v127
	v_mov_b32_e32 v116, v127
	v_mov_b32_e32 v115, v127
	v_mov_b32_e32 v114, v127
	v_mov_b32_e32 v113, v127
	v_mov_b32_e32 v112, v127
	v_mov_b32_e32 v111, v127
	v_mov_b32_e32 v110, v127
	v_mov_b32_e32 v109, v127
	v_mov_b32_e32 v108, v127
	s_waitcnt vmcnt(0)
	v_mov_b32_e32 v107, v127
	v_mov_b32_e32 v106, v127
	v_mov_b32_e32 v105, v127
	v_mov_b32_e32 v104, v127
	v_mov_b32_e32 v103, v127
	v_mov_b32_e32 v102, v127
	v_mov_b32_e32 v101, v127
	v_mov_b32_e32 v100, v127
	v_mov_b32_e32 v99, v127
	v_mov_b32_e32 v98, v127
	v_mov_b32_e32 v97, v127
	v_mov_b32_e32 v96, v127
	v_mov_b32_e32 v63, v127
	v_mov_b32_e32 v62, v127
	v_mov_b32_e32 v61, v127
	v_mov_b32_e32 v60, v127
	v_mov_b32_e32 v59, v127
	v_mov_b32_e32 v58, v127
	v_mov_b32_e32 v57, v127
	v_mov_b32_e32 v56, v127
	v_mov_b32_e32 v55, v127
	v_mov_b32_e32 v54, v127
	v_mov_b32_e32 v53, v127
	v_mov_b32_e32 v52, v127
	v_mov_b32_e32 v51, v127
	v_mov_b32_e32 v50, v127
	v_mov_b32_e32 v49, v127
	v_mov_b32_e32 v48, v127
	v_mov_b32_e32 v47, v127
	v_mov_b32_e32 v46, v127
	v_mov_b32_e32 v45, v127
	v_mov_b32_e32 v44, v127
	v_mov_b32_e32 v43, v127
	v_mov_b32_e32 v42, v127
	v_mov_b32_e32 v41, v127
	v_mov_b32_e32 v40, v127
	v_mov_b32_e32 v39, v127
	v_mov_b32_e32 v38, v127
	v_mov_b32_e32 v37, v127
	v_mov_b32_e32 v36, v127
	v_mov_b32_e32 v35, v127
	v_mov_b32_e32 v34, v127
	v_mov_b32_e32 v33, v127
	v_mov_b32_e32 v32, v127
	v_mov_b32_e32 v95, v127
	v_mov_b32_e32 v94, v127
	v_mov_b32_e32 v93, v127
	v_mov_b32_e32 v92, v127
	v_mov_b32_e32 v91, v127
	v_mov_b32_e32 v90, v127
	v_mov_b32_e32 v89, v127
	v_mov_b32_e32 v88, v127
	v_mov_b32_e32 v87, v127
	v_mov_b32_e32 v86, v127
	v_mov_b32_e32 v85, v127
	v_mov_b32_e32 v84, v127
	v_mov_b32_e32 v83, v127
	v_mov_b32_e32 v82, v127
	v_mov_b32_e32 v81, v127
	v_mov_b32_e32 v80, v127
	v_mov_b32_e32 v79, v127
	v_mov_b32_e32 v78, v127
	v_mov_b32_e32 v77, v127
	v_mov_b32_e32 v76, v127
	v_mov_b32_e32 v75, v127
	v_mov_b32_e32 v74, v127
	v_mov_b32_e32 v73, v127
	v_mov_b32_e32 v72, v127
	v_mov_b32_e32 v71, v127
	v_mov_b32_e32 v70, v127
	v_mov_b32_e32 v69, v127
	v_mov_b32_e32 v68, v127
	v_mov_b32_e32 v67, v127
	v_mov_b32_e32 v66, v127
	v_mov_b32_e32 v65, v127
	v_mov_b32_e32 v64, v127
	v_mov_b32_e32 v31, v127
	v_mov_b32_e32 v30, v127
	v_mov_b32_e32 v29, v127
	v_mov_b32_e32 v28, v127
	v_mov_b32_e32 v27, v127
	v_mov_b32_e32 v26, v127
	v_mov_b32_e32 v25, v127
	v_mov_b32_e32 v24, v127
	v_mov_b32_e32 v23, v127
	v_mov_b32_e32 v22, v127
	v_mov_b32_e32 v21, v127
	v_mov_b32_e32 v20, v127
	v_mov_b32_e32 v19, v127
	v_mov_b32_e32 v18, v127
	v_mov_b32_e32 v17, v127
	v_mov_b32_e32 v16, v127
	v_mov_b32_e32 v15, v127
	v_mov_b32_e32 v14, v127
	v_mov_b32_e32 v13, v127
	v_mov_b32_e32 v12, v127
	v_mov_b32_e32 v11, v127
	v_mov_b32_e32 v10, v127
	v_mov_b32_e32 v9, v127
	v_mov_b32_e32 v8, v127
	v_mov_b32_e32 v3, v127
	v_mov_b32_e32 v2, v127
	v_mov_b32_e32 v1, v127
	v_mov_b32_e32 v0, v127
	v_mov_b32_e32 v7, v127
	v_mov_b32_e32 v6, v127
	v_mov_b32_e32 v5, v127
	v_mov_b32_e32 v4, v127
	s_cbranch_vccnz .LBB0_364
	s_add_u32 s0, s0, 0x80
	s_addc_u32 s1, s1, 0
	s_add_u32 s40, s2, 0x100
	v_mov_b32_e32 v4, 0
	s_addc_u32 s41, s3, 0
	s_mov_b32 s2, 0
	v_mov_b32_e32 v5, v4
	v_mov_b32_e32 v6, v4
	v_mov_b32_e32 v7, v4
	v_mov_b32_e32 v0, v4
	v_mov_b32_e32 v1, v4
	v_mov_b32_e32 v2, v4
	v_mov_b32_e32 v3, v4
	v_mov_b32_e32 v8, v4
	v_mov_b32_e32 v9, v4
	v_mov_b32_e32 v10, v4
	v_mov_b32_e32 v11, v4
	v_mov_b32_e32 v12, v4
	v_mov_b32_e32 v13, v4
	v_mov_b32_e32 v14, v4
	v_mov_b32_e32 v15, v4
	v_mov_b32_e32 v16, v4
	v_mov_b32_e32 v17, v4
	v_mov_b32_e32 v18, v4
	v_mov_b32_e32 v19, v4
	v_mov_b32_e32 v20, v4
	v_mov_b32_e32 v21, v4
	v_mov_b32_e32 v22, v4
	v_mov_b32_e32 v23, v4
	v_mov_b32_e32 v24, v4
	v_mov_b32_e32 v25, v4
	v_mov_b32_e32 v26, v4
	v_mov_b32_e32 v27, v4
	v_mov_b32_e32 v28, v4
	v_mov_b32_e32 v29, v4
	v_mov_b32_e32 v30, v4
	v_mov_b32_e32 v31, v4
	v_mov_b32_e32 v64, v4
	v_mov_b32_e32 v65, v4
	v_mov_b32_e32 v66, v4
	v_mov_b32_e32 v67, v4
	v_mov_b32_e32 v68, v4
	v_mov_b32_e32 v69, v4
	v_mov_b32_e32 v70, v4
	v_mov_b32_e32 v71, v4
	v_mov_b32_e32 v72, v4
	v_mov_b32_e32 v73, v4
	v_mov_b32_e32 v74, v4
	v_mov_b32_e32 v75, v4
	v_mov_b32_e32 v76, v4
	v_mov_b32_e32 v77, v4
	v_mov_b32_e32 v78, v4
	v_mov_b32_e32 v79, v4
	v_mov_b32_e32 v80, v4
	v_mov_b32_e32 v81, v4
	v_mov_b32_e32 v82, v4
	v_mov_b32_e32 v83, v4
	v_mov_b32_e32 v84, v4
	v_mov_b32_e32 v85, v4
	v_mov_b32_e32 v86, v4
	v_mov_b32_e32 v87, v4
	v_mov_b32_e32 v88, v4
	v_mov_b32_e32 v89, v4
	v_mov_b32_e32 v90, v4
	v_mov_b32_e32 v91, v4
	v_mov_b32_e32 v92, v4
	v_mov_b32_e32 v93, v4
	v_mov_b32_e32 v94, v4
	v_mov_b32_e32 v95, v4
	v_mov_b32_e32 v32, v4
	v_mov_b32_e32 v33, v4
	v_mov_b32_e32 v34, v4
	v_mov_b32_e32 v35, v4
	v_mov_b32_e32 v36, v4
	v_mov_b32_e32 v37, v4
	v_mov_b32_e32 v38, v4
	v_mov_b32_e32 v39, v4
	v_mov_b32_e32 v40, v4
	v_mov_b32_e32 v41, v4
	v_mov_b32_e32 v42, v4
	v_mov_b32_e32 v43, v4
	v_mov_b32_e32 v44, v4
	v_mov_b32_e32 v45, v4
	v_mov_b32_e32 v46, v4
	v_mov_b32_e32 v47, v4
	v_mov_b32_e32 v48, v4
	v_mov_b32_e32 v49, v4
	v_mov_b32_e32 v50, v4
	v_mov_b32_e32 v51, v4
	v_mov_b32_e32 v52, v4
	v_mov_b32_e32 v53, v4
	v_mov_b32_e32 v54, v4
	v_mov_b32_e32 v55, v4
	v_mov_b32_e32 v56, v4
	v_mov_b32_e32 v57, v4
	v_mov_b32_e32 v58, v4
	v_mov_b32_e32 v59, v4
	v_mov_b32_e32 v60, v4
	v_mov_b32_e32 v61, v4
	v_mov_b32_e32 v62, v4
	v_mov_b32_e32 v63, v4
	v_mov_b32_e32 v96, v4
	v_mov_b32_e32 v97, v4
	v_mov_b32_e32 v98, v4
	v_mov_b32_e32 v99, v4
	v_mov_b32_e32 v100, v4
	v_mov_b32_e32 v101, v4
	v_mov_b32_e32 v102, v4
	v_mov_b32_e32 v103, v4
	v_mov_b32_e32 v104, v4
	v_mov_b32_e32 v105, v4
	v_mov_b32_e32 v106, v4
	v_mov_b32_e32 v107, v4
	v_mov_b32_e32 v108, v4
	v_mov_b32_e32 v109, v4
	v_mov_b32_e32 v110, v4
	v_mov_b32_e32 v111, v4
	v_mov_b32_e32 v112, v4
	v_mov_b32_e32 v113, v4
	v_mov_b32_e32 v114, v4
	v_mov_b32_e32 v115, v4
	v_mov_b32_e32 v116, v4
	v_mov_b32_e32 v117, v4
	v_mov_b32_e32 v118, v4
	v_mov_b32_e32 v119, v4
	v_mov_b32_e32 v120, v4
	v_mov_b32_e32 v121, v4
	v_mov_b32_e32 v122, v4
	v_mov_b32_e32 v123, v4
	v_mov_b32_e32 v124, v4
	v_mov_b32_e32 v125, v4
	v_mov_b32_e32 v126, v4
	v_mov_b32_e32 v127, v4
	v_readfirstlane_b32 s101, v211
	s_cmp_ge_u32 s101, 0x100
	s_cbranch_scc0 .Lprio_skip9
	s_setprio 1

; template <class Epi, class Sched, bool ALIGN_EPI = false, bool SP2 = false>
; __device__ __forceinline__ void gemm_phase(PG8_LAS unsigned char* lds, const Gemm g, const Sched& S, const Epi& E) {
;     ...
;         if (!has_next) break;
; #pragma unroll
;         for (int a = 0; a < 2; ++a)
; #pragma unroll
;             for (int b = 0; b < 2; ++b)
; #pragma unroll
;                 for (int m = 0; m < 4; ++m)
; #pragma unroll
;                     for (int n = 0; n < 2; ++n) acc[a][b][m][n] = (f32x4){0.f, 0.f, 0.f, 0.f};
;         cur = nxt; cA = nA; cB = nB; ++ui;
.LBB0_390:
	v_mov_b32_e32 v123, 0
	s_andn2_b64 vcc, exec, s[50:51]
	v_mov_b32_e32 v122, v123
	v_mov_b32_e32 v121, v123
	v_mov_b32_e32 v120, v123
	v_mov_b32_e32 v127, v123
	v_mov_b32_e32 v126, v123
	v_mov_b32_e32 v125, v123
	v_mov_b32_e32 v124, v123
	v_mov_b32_e32 v119, v123
	v_mov_b32_e32 v118, v123
	v_mov_b32_e32 v117, v123
	v_mov_b32_e32 v116, v123
	v_mov_b32_e32 v115, v123
	v_mov_b32_e32 v114, v123
	v_mov_b32_e32 v113, v123
	v_mov_b32_e32 v112, v123
	v_mov_b32_e32 v111, v123
	v_mov_b32_e32 v110, v123
	v_mov_b32_e32 v109, v123
	v_mov_b32_e32 v108, v123
	s_waitcnt vmcnt(0)
	v_mov_b32_e32 v107, v123
	v_mov_b32_e32 v106, v123
	v_mov_b32_e32 v105, v123
	v_mov_b32_e32 v104, v123
	v_mov_b32_e32 v103, v123
	v_mov_b32_e32 v102, v123
	v_mov_b32_e32 v101, v123
	v_mov_b32_e32 v100, v123
	v_mov_b32_e32 v99, v123
	v_mov_b32_e32 v98, v123
	v_mov_b32_e32 v97, v123
	v_mov_b32_e32 v96, v123
	v_mov_b32_e32 v63, v123
	v_mov_b32_e32 v62, v123
	v_mov_b32_e32 v61, v123
	v_mov_b32_e32 v60, v123
	v_mov_b32_e32 v59, v123
	v_mov_b32_e32 v58, v123
	v_mov_b32_e32 v57, v123
	v_mov_b32_e32 v56, v123
	v_mov_b32_e32 v55, v123
	v_mov_b32_e32 v54, v123
	v_mov_b32_e32 v53, v123
	v_mov_b32_e32 v52, v123
	v_mov_b32_e32 v51, v123
	v_mov_b32_e32 v50, v123
	v_mov_b32_e32 v49, v123
	v_mov_b32_e32 v48, v123
	v_mov_b32_e32 v47, v123
	v_mov_b32_e32 v46, v123
	v_mov_b32_e32 v45, v123
	v_mov_b32_e32 v44, v123
	v_mov_b32_e32 v43, v123
	v_mov_b32_e32 v42, v123
	v_mov_b32_e32 v41, v123
	v_mov_b32_e32 v40, v123
	v_mov_b32_e32 v39, v123
	v_mov_b32_e32 v38, v123
	v_mov_b32_e32 v37, v123
	v_mov_b32_e32 v36, v123
	v_mov_b32_e32 v35, v123
	v_mov_b32_e32 v34, v123
	v_mov_b32_e32 v33, v123
	v_mov_b32_e32 v32, v123
	v_mov_b32_e32 v95, v123
	v_mov_b32_e32 v94, v123
	v_mov_b32_e32 v93, v123
	v_mov_b32_e32 v92, v123
	v_mov_b32_e32 v91, v123
	v_mov_b32_e32 v90, v123
	v_mov_b32_e32 v89, v123
	v_mov_b32_e32 v88, v123
	v_mov_b32_e32 v87, v123
	v_mov_b32_e32 v86, v123
	v_mov_b32_e32 v85, v123
	v_mov_b32_e32 v84, v123
	v_mov_b32_e32 v83, v123
	v_mov_b32_e32 v82, v123
	v_mov_b32_e32 v81, v123
	v_mov_b32_e32 v80, v123
	v_mov_b32_e32 v79, v123
	v_mov_b32_e32 v78, v123
	v_mov_b32_e32 v77, v123
	v_mov_b32_e32 v76, v123
	v_mov_b32_e32 v75, v123
	v_mov_b32_e32 v74, v123
	v_mov_b32_e32 v73, v123
	v_mov_b32_e32 v72, v123
	v_mov_b32_e32 v71, v123
	v_mov_b32_e32 v70, v123
	v_mov_b32_e32 v69, v123
	v_mov_b32_e32 v68, v123
	v_mov_b32_e32 v67, v123
	v_mov_b32_e32 v66, v123
	v_mov_b32_e32 v65, v123
	v_mov_b32_e32 v64, v123
	v_mov_b32_e32 v31, v123
	v_mov_b32_e32 v30, v123
	v_mov_b32_e32 v29, v123
	v_mov_b32_e32 v28, v123
	v_mov_b32_e32 v27, v123
	v_mov_b32_e32 v26, v123
	v_mov_b32_e32 v25, v123
	v_mov_b32_e32 v24, v123
	v_mov_b32_e32 v23, v123
	v_mov_b32_e32 v22, v123
	v_mov_b32_e32 v21, v123
	v_mov_b32_e32 v20, v123
	v_mov_b32_e32 v19, v123
	v_mov_b32_e32 v18, v123
	v_mov_b32_e32 v17, v123
	v_mov_b32_e32 v16, v123
	v_mov_b32_e32 v15, v123
	v_mov_b32_e32 v14, v123
	v_mov_b32_e32 v13, v123
	v_mov_b32_e32 v12, v123
	v_mov_b32_e32 v11, v123
	v_mov_b32_e32 v10, v123
	v_mov_b32_e32 v9, v123
	v_mov_b32_e32 v8, v123
	v_mov_b32_e32 v7, v123
	v_mov_b32_e32 v6, v123
	v_mov_b32_e32 v5, v123
	v_mov_b32_e32 v4, v123
	v_mov_b32_e32 v3, v123
	v_mov_b32_e32 v2, v123
	v_mov_b32_e32 v1, v123
	v_mov_b32_e32 v0, v123
	s_cbranch_vccnz .LBB0_393
	s_add_u32 s0, s0, 0x80
	s_addc_u32 s1, s1, 0
	s_add_u32 s40, s2, 0x100
	v_mov_b32_e32 v0, 0
	s_addc_u32 s41, s3, 0
	s_mov_b32 s2, 0
	v_mov_b32_e32 v1, v0
	v_mov_b32_e32 v2, v0
	v_mov_b32_e32 v3, v0
	v_mov_b32_e32 v4, v0
	v_mov_b32_e32 v5, v0
	v_mov_b32_e32 v6, v0
	v_mov_b32_e32 v7, v0
	v_mov_b32_e32 v8, v0
	v_mov_b32_e32 v9, v0
	v_mov_b32_e32 v10, v0
	v_mov_b32_e32 v11, v0
	v_mov_b32_e32 v12, v0
	v_mov_b32_e32 v13, v0
	v_mov_b32_e32 v14, v0
	v_mov_b32_e32 v15, v0
	v_mov_b32_e32 v16, v0
	v_mov_b32_e32 v17, v0
	v_mov_b32_e32 v18, v0
	v_mov_b32_e32 v19, v0
	v_mov_b32_e32 v20, v0
	v_mov_b32_e32 v21, v0
	v_mov_b32_e32 v22, v0
	v_mov_b32_e32 v23, v0
	v_mov_b32_e32 v24, v0
	v_mov_b32_e32 v25, v0
	v_mov_b32_e32 v26, v0
	v_mov_b32_e32 v27, v0
	v_mov_b32_e32 v28, v0
	v_mov_b32_e32 v29, v0
	v_mov_b32_e32 v30, v0
	v_mov_b32_e32 v31, v0
	v_mov_b32_e32 v64, v0
	v_mov_b32_e32 v65, v0
	v_mov_b32_e32 v66, v0
	v_mov_b32_e32 v67, v0
	v_mov_b32_e32 v68, v0
	v_mov_b32_e32 v69, v0
	v_mov_b32_e32 v70, v0
	v_mov_b32_e32 v71, v0
	v_mov_b32_e32 v72, v0
	v_mov_b32_e32 v73, v0
	v_mov_b32_e32 v74, v0
	v_mov_b32_e32 v75, v0
	v_mov_b32_e32 v76, v0
	v_mov_b32_e32 v77, v0
	v_mov_b32_e32 v78, v0
	v_mov_b32_e32 v79, v0
	v_mov_b32_e32 v80, v0
	v_mov_b32_e32 v81, v0
	v_mov_b32_e32 v82, v0
	v_mov_b32_e32 v83, v0
	v_mov_b32_e32 v84, v0
	v_mov_b32_e32 v85, v0
	v_mov_b32_e32 v86, v0
	v_mov_b32_e32 v87, v0
	v_mov_b32_e32 v88, v0
	v_mov_b32_e32 v89, v0
	v_mov_b32_e32 v90, v0
	v_mov_b32_e32 v91, v0
	v_mov_b32_e32 v92, v0
	v_mov_b32_e32 v93, v0
	v_mov_b32_e32 v94, v0
	v_mov_b32_e32 v95, v0
	v_mov_b32_e32 v32, v0
	v_mov_b32_e32 v33, v0
	v_mov_b32_e32 v34, v0
	v_mov_b32_e32 v35, v0
	v_mov_b32_e32 v36, v0
	v_mov_b32_e32 v37, v0
	v_mov_b32_e32 v38, v0
	v_mov_b32_e32 v39, v0
	v_mov_b32_e32 v40, v0
	v_mov_b32_e32 v41, v0
	v_mov_b32_e32 v42, v0
	v_mov_b32_e32 v43, v0
	v_mov_b32_e32 v44, v0
	v_mov_b32_e32 v45, v0
	v_mov_b32_e32 v46, v0
	v_mov_b32_e32 v47, v0
	v_mov_b32_e32 v48, v0
	v_mov_b32_e32 v49, v0
	v_mov_b32_e32 v50, v0
	v_mov_b32_e32 v51, v0
	v_mov_b32_e32 v52, v0
	v_mov_b32_e32 v53, v0
	v_mov_b32_e32 v54, v0
	v_mov_b32_e32 v55, v0
	v_mov_b32_e32 v56, v0
	v_mov_b32_e32 v57, v0
	v_mov_b32_e32 v58, v0
	v_mov_b32_e32 v59, v0
	v_mov_b32_e32 v60, v0
	v_mov_b32_e32 v61, v0
	v_mov_b32_e32 v62, v0
	v_mov_b32_e32 v63, v0
	v_mov_b32_e32 v96, v0
	v_mov_b32_e32 v97, v0
	v_mov_b32_e32 v98, v0
	v_mov_b32_e32 v99, v0
	v_mov_b32_e32 v100, v0
	v_mov_b32_e32 v101, v0
	v_mov_b32_e32 v102, v0
	v_mov_b32_e32 v103, v0
	v_mov_b32_e32 v104, v0
	v_mov_b32_e32 v105, v0
	v_mov_b32_e32 v106, v0
	v_mov_b32_e32 v107, v0
	v_mov_b32_e32 v108, v0
	v_mov_b32_e32 v109, v0
	v_mov_b32_e32 v110, v0
	v_mov_b32_e32 v111, v0
	v_mov_b32_e32 v112, v0
	v_mov_b32_e32 v113, v0
	v_mov_b32_e32 v114, v0
	v_mov_b32_e32 v115, v0
	v_mov_b32_e32 v116, v0
	v_mov_b32_e32 v117, v0
	v_mov_b32_e32 v118, v0
	v_mov_b32_e32 v119, v0
	v_mov_b32_e32 v124, v0
	v_mov_b32_e32 v125, v0
	v_mov_b32_e32 v126, v0
	v_mov_b32_e32 v127, v0
	v_mov_b32_e32 v120, v0
	v_mov_b32_e32 v121, v0
	v_mov_b32_e32 v122, v0
	v_mov_b32_e32 v123, v0
	v_readfirstlane_b32 s101, v211
	s_cmp_ge_u32 s101, 0x100
	s_cbranch_scc0 .Lprio_skip8
	s_setprio 1

; template <class Epi, class Sched, bool ALIGN_EPI = false, bool SP2 = false>
; __device__ __forceinline__ void gemm_phase(PG8_LAS unsigned char* lds, const Gemm g, const Sched& S, const Epi& E) {
;     ...
;         if (!has_next) break;
; #pragma unroll
;         for (int a = 0; a < 2; ++a)
; #pragma unroll
;             for (int b = 0; b < 2; ++b)
; #pragma unroll
;                 for (int m = 0; m < 4; ++m)
; #pragma unroll
;                     for (int n = 0; n < 2; ++n) acc[a][b][m][n] = (f32x4){0.f, 0.f, 0.f, 0.f};
;         cur = nxt; cA = nA; cB = nB; ++ui;
.LBB0_419:
	v_mov_b32_e32 v123, 0
	s_andn2_b64 vcc, exec, s[26:27]
	v_mov_b32_e32 v122, v123
	v_mov_b32_e32 v121, v123
	v_mov_b32_e32 v120, v123
	v_mov_b32_e32 v127, v123
	v_mov_b32_e32 v126, v123
	v_mov_b32_e32 v125, v123
	v_mov_b32_e32 v124, v123
	v_mov_b32_e32 v119, v123
	v_mov_b32_e32 v118, v123
	v_mov_b32_e32 v117, v123
	v_mov_b32_e32 v116, v123
	v_mov_b32_e32 v115, v123
	v_mov_b32_e32 v114, v123
	v_mov_b32_e32 v113, v123
	v_mov_b32_e32 v112, v123
	v_mov_b32_e32 v111, v123
	v_mov_b32_e32 v110, v123
	v_mov_b32_e32 v109, v123
	v_mov_b32_e32 v108, v123
	s_waitcnt vmcnt(0)
	v_mov_b32_e32 v107, v123
	v_mov_b32_e32 v106, v123
	v_mov_b32_e32 v105, v123
	v_mov_b32_e32 v104, v123
	v_mov_b32_e32 v103, v123
	v_mov_b32_e32 v102, v123
	v_mov_b32_e32 v101, v123
	v_mov_b32_e32 v100, v123
	v_mov_b32_e32 v99, v123
	v_mov_b32_e32 v98, v123
	v_mov_b32_e32 v97, v123
	v_mov_b32_e32 v96, v123
	v_mov_b32_e32 v63, v123
	v_mov_b32_e32 v62, v123
	v_mov_b32_e32 v61, v123
	v_mov_b32_e32 v60, v123
	v_mov_b32_e32 v59, v123
	v_mov_b32_e32 v58, v123
	v_mov_b32_e32 v57, v123
	v_mov_b32_e32 v56, v123
	v_mov_b32_e32 v55, v123
	v_mov_b32_e32 v54, v123
	v_mov_b32_e32 v53, v123
	v_mov_b32_e32 v52, v123
	v_mov_b32_e32 v51, v123
	v_mov_b32_e32 v50, v123
	v_mov_b32_e32 v49, v123
	v_mov_b32_e32 v48, v123
	v_mov_b32_e32 v47, v123
	v_mov_b32_e32 v46, v123
	v_mov_b32_e32 v45, v123
	v_mov_b32_e32 v44, v123
	v_mov_b32_e32 v43, v123
	v_mov_b32_e32 v42, v123
	v_mov_b32_e32 v41, v123
	v_mov_b32_e32 v40, v123
	v_mov_b32_e32 v39, v123
	v_mov_b32_e32 v38, v123
	v_mov_b32_e32 v37, v123
	v_mov_b32_e32 v36, v123
	v_mov_b32_e32 v35, v123
	v_mov_b32_e32 v34, v123
	v_mov_b32_e32 v33, v123
	v_mov_b32_e32 v32, v123
	v_mov_b32_e32 v95, v123
	v_mov_b32_e32 v94, v123
	v_mov_b32_e32 v93, v123
	v_mov_b32_e32 v92, v123
	v_mov_b32_e32 v91, v123
	v_mov_b32_e32 v90, v123
	v_mov_b32_e32 v89, v123
	v_mov_b32_e32 v88, v123
	v_mov_b32_e32 v87, v123
	v_mov_b32_e32 v86, v123
	v_mov_b32_e32 v85, v123
	v_mov_b32_e32 v84, v123
	v_mov_b32_e32 v83, v123
	v_mov_b32_e32 v82, v123
	v_mov_b32_e32 v81, v123
	v_mov_b32_e32 v80, v123
	v_mov_b32_e32 v79, v123
	v_mov_b32_e32 v78, v123
	v_mov_b32_e32 v77, v123
	v_mov_b32_e32 v76, v123
	v_mov_b32_e32 v75, v123
	v_mov_b32_e32 v74, v123
	v_mov_b32_e32 v73, v123
	v_mov_b32_e32 v72, v123
	v_mov_b32_e32 v71, v123
	v_mov_b32_e32 v70, v123
	v_mov_b32_e32 v69, v123
	v_mov_b32_e32 v68, v123
	v_mov_b32_e32 v67, v123
	v_mov_b32_e32 v66, v123
	v_mov_b32_e32 v65, v123
	v_mov_b32_e32 v64, v123
	v_mov_b32_e32 v31, v123
	v_mov_b32_e32 v30, v123
	v_mov_b32_e32 v29, v123
	v_mov_b32_e32 v28, v123
	v_mov_b32_e32 v27, v123
	v_mov_b32_e32 v26, v123
	v_mov_b32_e32 v25, v123
	v_mov_b32_e32 v24, v123
	v_mov_b32_e32 v23, v123
	v_mov_b32_e32 v22, v123
	v_mov_b32_e32 v21, v123
	v_mov_b32_e32 v20, v123
	v_mov_b32_e32 v19, v123
	v_mov_b32_e32 v18, v123
	v_mov_b32_e32 v17, v123
	v_mov_b32_e32 v16, v123
	v_mov_b32_e32 v15, v123
	v_mov_b32_e32 v14, v123
	v_mov_b32_e32 v13, v123
	v_mov_b32_e32 v12, v123
	v_mov_b32_e32 v11, v123
	v_mov_b32_e32 v10, v123
	v_mov_b32_e32 v9, v123
	v_mov_b32_e32 v8, v123
	v_mov_b32_e32 v7, v123
	v_mov_b32_e32 v6, v123
	v_mov_b32_e32 v5, v123
	v_mov_b32_e32 v4, v123
	v_mov_b32_e32 v3, v123
	v_mov_b32_e32 v2, v123
	v_mov_b32_e32 v1, v123
	v_mov_b32_e32 v0, v123
	s_cbranch_vccnz .LBB0_422
	s_add_u32 s0, s0, 0x80
	s_addc_u32 s1, s1, 0
	s_add_u32 s40, s2, 0x100
	v_mov_b32_e32 v0, 0
	s_addc_u32 s41, s3, 0
	s_mov_b32 s2, 0
	v_mov_b32_e32 v1, v0
	v_mov_b32_e32 v2, v0
	v_mov_b32_e32 v3, v0
	v_mov_b32_e32 v4, v0
	v_mov_b32_e32 v5, v0
	v_mov_b32_e32 v6, v0
	v_mov_b32_e32 v7, v0
	v_mov_b32_e32 v8, v0
	v_mov_b32_e32 v9, v0
	v_mov_b32_e32 v10, v0
	v_mov_b32_e32 v11, v0
	v_mov_b32_e32 v12, v0
	v_mov_b32_e32 v13, v0
	v_mov_b32_e32 v14, v0
	v_mov_b32_e32 v15, v0
	v_mov_b32_e32 v16, v0
	v_mov_b32_e32 v17, v0
	v_mov_b32_e32 v18, v0
	v_mov_b32_e32 v19, v0
	v_mov_b32_e32 v20, v0
	v_mov_b32_e32 v21, v0
	v_mov_b32_e32 v22, v0
	v_mov_b32_e32 v23, v0
	v_mov_b32_e32 v24, v0
	v_mov_b32_e32 v25, v0
	v_mov_b32_e32 v26, v0
	v_mov_b32_e32 v27, v0
	v_mov_b32_e32 v28, v0
	v_mov_b32_e32 v29, v0
	v_mov_b32_e32 v30, v0
	v_mov_b32_e32 v31, v0
	v_mov_b32_e32 v64, v0
	v_mov_b32_e32 v65, v0
	v_mov_b32_e32 v66, v0
	v_mov_b32_e32 v67, v0
	v_mov_b32_e32 v68, v0
	v_mov_b32_e32 v69, v0
	v_mov_b32_e32 v70, v0
	v_mov_b32_e32 v71, v0
	v_mov_b32_e32 v72, v0
	v_mov_b32_e32 v73, v0
	v_mov_b32_e32 v74, v0
	v_mov_b32_e32 v75, v0
	v_mov_b32_e32 v76, v0
	v_mov_b32_e32 v77, v0
	v_mov_b32_e32 v78, v0
	v_mov_b32_e32 v79, v0
	v_mov_b32_e32 v80, v0
	v_mov_b32_e32 v81, v0
	v_mov_b32_e32 v82, v0
	v_mov_b32_e32 v83, v0
	v_mov_b32_e32 v84, v0
	v_mov_b32_e32 v85, v0
	v_mov_b32_e32 v86, v0
	v_mov_b32_e32 v87, v0
	v_mov_b32_e32 v88, v0
	v_mov_b32_e32 v89, v0
	v_mov_b32_e32 v90, v0
	v_mov_b32_e32 v91, v0
	v_mov_b32_e32 v92, v0
	v_mov_b32_e32 v93, v0
	v_mov_b32_e32 v94, v0
	v_mov_b32_e32 v95, v0
	v_mov_b32_e32 v32, v0
	v_mov_b32_e32 v33, v0
	v_mov_b32_e32 v34, v0
	v_mov_b32_e32 v35, v0
	v_mov_b32_e32 v36, v0
	v_mov_b32_e32 v37, v0
	v_mov_b32_e32 v38, v0
	v_mov_b32_e32 v39, v0
	v_mov_b32_e32 v40, v0
	v_mov_b32_e32 v41, v0
	v_mov_b32_e32 v42, v0
	v_mov_b32_e32 v43, v0
	v_mov_b32_e32 v44, v0
	v_mov_b32_e32 v45, v0
	v_mov_b32_e32 v46, v0
	v_mov_b32_e32 v47, v0
	v_mov_b32_e32 v48, v0
	v_mov_b32_e32 v49, v0
	v_mov_b32_e32 v50, v0
	v_mov_b32_e32 v51, v0
	v_mov_b32_e32 v52, v0
	v_mov_b32_e32 v53, v0
	v_mov_b32_e32 v54, v0
	v_mov_b32_e32 v55, v0
	v_mov_b32_e32 v56, v0
	v_mov_b32_e32 v57, v0
	v_mov_b32_e32 v58, v0
	v_mov_b32_e32 v59, v0
	v_mov_b32_e32 v60, v0
	v_mov_b32_e32 v61, v0
	v_mov_b32_e32 v62, v0
	v_mov_b32_e32 v63, v0
	v_mov_b32_e32 v96, v0
	v_mov_b32_e32 v97, v0
	v_mov_b32_e32 v98, v0
	v_mov_b32_e32 v99, v0
	v_mov_b32_e32 v100, v0
	v_mov_b32_e32 v101, v0
	v_mov_b32_e32 v102, v0
	v_mov_b32_e32 v103, v0
	v_mov_b32_e32 v104, v0
	v_mov_b32_e32 v105, v0
	v_mov_b32_e32 v106, v0
	v_mov_b32_e32 v107, v0
	v_mov_b32_e32 v108, v0
	v_mov_b32_e32 v109, v0
	v_mov_b32_e32 v110, v0
	v_mov_b32_e32 v111, v0
	v_mov_b32_e32 v112, v0
	v_mov_b32_e32 v113, v0
	v_mov_b32_e32 v114, v0
	v_mov_b32_e32 v115, v0
	v_mov_b32_e32 v116, v0
	v_mov_b32_e32 v117, v0
	v_mov_b32_e32 v118, v0
	v_mov_b32_e32 v119, v0
	v_mov_b32_e32 v124, v0
	v_mov_b32_e32 v125, v0
	v_mov_b32_e32 v126, v0
	v_mov_b32_e32 v127, v0
	v_mov_b32_e32 v120, v0
	v_mov_b32_e32 v121, v0
	v_mov_b32_e32 v122, v0
	v_mov_b32_e32 v123, v0
	v_readfirstlane_b32 s101, v211
	s_cmp_ge_u32 s101, 0x100
	s_cbranch_scc0 .Lprio_skip7
	s_setprio 1

; template <class Epi, class Sched, bool ALIGN_EPI = false, bool SP2 = false>
; __device__ __forceinline__ void gemm_phase(PG8_LAS unsigned char* lds, const Gemm g, const Sched& S, const Epi& E) {
;     ...
;         if (!has_next) break;
; #pragma unroll
;         for (int a = 0; a < 2; ++a)
; #pragma unroll
;             for (int b = 0; b < 2; ++b)
; #pragma unroll
;                 for (int m = 0; m < 4; ++m)
; #pragma unroll
;                     for (int n = 0; n < 2; ++n) acc[a][b][m][n] = (f32x4){0.f, 0.f, 0.f, 0.f};
;         cur = nxt; cA = nA; cB = nB; ++ui;
.LBB0_442:
	v_mov_b32_e32 v131, 0
	s_andn2_b64 vcc, exec, s[70:71]
	v_mov_b32_e32 v130, v131
	s_waitcnt vmcnt(0)
	v_mov_b32_e32 v129, v131
	v_mov_b32_e32 v128, v131
	v_mov_b32_e32 v135, v131
	v_mov_b32_e32 v134, v131
	v_mov_b32_e32 v133, v131
	v_mov_b32_e32 v132, v131
	v_mov_b32_e32 v127, v131
	v_mov_b32_e32 v126, v131
	v_mov_b32_e32 v125, v131
	v_mov_b32_e32 v124, v131
	v_mov_b32_e32 v123, v131
	v_mov_b32_e32 v122, v131
	v_mov_b32_e32 v121, v131
	v_mov_b32_e32 v120, v131
	v_mov_b32_e32 v119, v131
	v_mov_b32_e32 v118, v131
	v_mov_b32_e32 v117, v131
	v_mov_b32_e32 v116, v131
	v_mov_b32_e32 v115, v131
	v_mov_b32_e32 v114, v131
	v_mov_b32_e32 v113, v131
	v_mov_b32_e32 v112, v131
	v_mov_b32_e32 v111, v131
	v_mov_b32_e32 v110, v131
	v_mov_b32_e32 v109, v131
	v_mov_b32_e32 v108, v131
	v_mov_b32_e32 v107, v131
	v_mov_b32_e32 v106, v131
	v_mov_b32_e32 v105, v131
	v_mov_b32_e32 v104, v131
	v_mov_b32_e32 v63, v131
	v_mov_b32_e32 v62, v131
	v_mov_b32_e32 v61, v131
	v_mov_b32_e32 v60, v131
	v_mov_b32_e32 v59, v131
	v_mov_b32_e32 v58, v131
	v_mov_b32_e32 v57, v131
	v_mov_b32_e32 v56, v131
	v_mov_b32_e32 v55, v131
	v_mov_b32_e32 v54, v131
	v_mov_b32_e32 v53, v131
	v_mov_b32_e32 v52, v131
	v_mov_b32_e32 v51, v131
	v_mov_b32_e32 v50, v131
	v_mov_b32_e32 v49, v131
	v_mov_b32_e32 v48, v131
	v_mov_b32_e32 v47, v131
	v_mov_b32_e32 v46, v131
	v_mov_b32_e32 v45, v131
	v_mov_b32_e32 v44, v131
	v_mov_b32_e32 v43, v131
	v_mov_b32_e32 v42, v131
	v_mov_b32_e32 v41, v131
	v_mov_b32_e32 v40, v131
	v_mov_b32_e32 v39, v131
	v_mov_b32_e32 v38, v131
	v_mov_b32_e32 v37, v131
	v_mov_b32_e32 v36, v131
	v_mov_b32_e32 v35, v131
	v_mov_b32_e32 v34, v131
	v_mov_b32_e32 v33, v131
	v_mov_b32_e32 v32, v131
	v_mov_b32_e32 v103, v131
	v_mov_b32_e32 v102, v131
	v_mov_b32_e32 v101, v131
	v_mov_b32_e32 v100, v131
	v_mov_b32_e32 v99, v131
	v_mov_b32_e32 v98, v131
	v_mov_b32_e32 v97, v131
	v_mov_b32_e32 v96, v131
	v_mov_b32_e32 v87, v131
	v_mov_b32_e32 v86, v131
	v_mov_b32_e32 v85, v131
	v_mov_b32_e32 v84, v131
	v_mov_b32_e32 v83, v131
	v_mov_b32_e32 v82, v131
	v_mov_b32_e32 v81, v131
	v_mov_b32_e32 v80, v131
	v_mov_b32_e32 v79, v131
	v_mov_b32_e32 v78, v131
	v_mov_b32_e32 v77, v131
	v_mov_b32_e32 v76, v131
	v_mov_b32_e32 v75, v131
	v_mov_b32_e32 v74, v131
	v_mov_b32_e32 v73, v131
	v_mov_b32_e32 v72, v131
	v_mov_b32_e32 v71, v131
	v_mov_b32_e32 v70, v131
	v_mov_b32_e32 v69, v131
	v_mov_b32_e32 v68, v131
	v_mov_b32_e32 v67, v131
	v_mov_b32_e32 v66, v131
	v_mov_b32_e32 v65, v131
	v_mov_b32_e32 v64, v131
	v_mov_b32_e32 v31, v131
	v_mov_b32_e32 v30, v131
	v_mov_b32_e32 v29, v131
	v_mov_b32_e32 v28, v131
	v_mov_b32_e32 v27, v131
	v_mov_b32_e32 v26, v131
	v_mov_b32_e32 v25, v131
	v_mov_b32_e32 v24, v131
	v_mov_b32_e32 v23, v131
	v_mov_b32_e32 v22, v131
	v_mov_b32_e32 v21, v131
	v_mov_b32_e32 v20, v131
	v_mov_b32_e32 v19, v131
	v_mov_b32_e32 v18, v131
	v_mov_b32_e32 v17, v131
	v_mov_b32_e32 v16, v131
	v_mov_b32_e32 v15, v131
	v_mov_b32_e32 v14, v131
	v_mov_b32_e32 v13, v131
	v_mov_b32_e32 v12, v131
	v_mov_b32_e32 v11, v131
	v_mov_b32_e32 v10, v131
	v_mov_b32_e32 v9, v131
	v_mov_b32_e32 v8, v131
	v_mov_b32_e32 v7, v131
	v_mov_b32_e32 v6, v131
	v_mov_b32_e32 v5, v131
	v_mov_b32_e32 v4, v131
	v_mov_b32_e32 v3, v131
	v_mov_b32_e32 v2, v131
	v_mov_b32_e32 v1, v131
	v_mov_b32_e32 v0, v131
	s_cbranch_vccnz .LBB0_445
	s_add_u32 s0, s0, 0x80
	s_addc_u32 s1, s1, 0
	s_add_u32 s6, s2, 0x100
	v_mov_b32_e32 v0, 0
	s_addc_u32 s7, s3, 0
	s_mov_b32 s2, 0
	v_mov_b32_e32 v1, v0
	v_mov_b32_e32 v2, v0
	v_mov_b32_e32 v3, v0
	v_mov_b32_e32 v4, v0
	v_mov_b32_e32 v5, v0
	v_mov_b32_e32 v6, v0
	v_mov_b32_e32 v7, v0
	v_mov_b32_e32 v8, v0
	v_mov_b32_e32 v9, v0
	v_mov_b32_e32 v10, v0
	v_mov_b32_e32 v11, v0
	v_mov_b32_e32 v12, v0
	v_mov_b32_e32 v13, v0
	v_mov_b32_e32 v14, v0
	v_mov_b32_e32 v15, v0
	v_mov_b32_e32 v16, v0
	v_mov_b32_e32 v17, v0
	v_mov_b32_e32 v18, v0
	v_mov_b32_e32 v19, v0
	v_mov_b32_e32 v20, v0
	v_mov_b32_e32 v21, v0
	v_mov_b32_e32 v22, v0
	v_mov_b32_e32 v23, v0
	v_mov_b32_e32 v24, v0
	v_mov_b32_e32 v25, v0
	v_mov_b32_e32 v26, v0
	v_mov_b32_e32 v27, v0
	v_mov_b32_e32 v28, v0
	v_mov_b32_e32 v29, v0
	v_mov_b32_e32 v30, v0
	v_mov_b32_e32 v31, v0
	v_mov_b32_e32 v64, v0
	v_mov_b32_e32 v65, v0
	v_mov_b32_e32 v66, v0
	v_mov_b32_e32 v67, v0
	v_mov_b32_e32 v68, v0
	v_mov_b32_e32 v69, v0
	v_mov_b32_e32 v70, v0
	v_mov_b32_e32 v71, v0
	v_mov_b32_e32 v72, v0
	v_mov_b32_e32 v73, v0
	v_mov_b32_e32 v74, v0
	v_mov_b32_e32 v75, v0
	v_mov_b32_e32 v76, v0
	v_mov_b32_e32 v77, v0
	v_mov_b32_e32 v78, v0
	v_mov_b32_e32 v79, v0
	v_mov_b32_e32 v80, v0
	v_mov_b32_e32 v81, v0
	v_mov_b32_e32 v82, v0
	v_mov_b32_e32 v83, v0
	v_mov_b32_e32 v84, v0
	v_mov_b32_e32 v85, v0
	v_mov_b32_e32 v86, v0
	v_mov_b32_e32 v87, v0
	v_mov_b32_e32 v96, v0
	v_mov_b32_e32 v97, v0
	v_mov_b32_e32 v98, v0
	v_mov_b32_e32 v99, v0
	v_mov_b32_e32 v100, v0
	v_mov_b32_e32 v101, v0
	v_mov_b32_e32 v102, v0
	v_mov_b32_e32 v103, v0
	v_mov_b32_e32 v32, v0
	v_mov_b32_e32 v33, v0
	v_mov_b32_e32 v34, v0
	v_mov_b32_e32 v35, v0
	v_mov_b32_e32 v36, v0
	v_mov_b32_e32 v37, v0
	v_mov_b32_e32 v38, v0
	v_mov_b32_e32 v39, v0
	v_mov_b32_e32 v40, v0
	v_mov_b32_e32 v41, v0
	v_mov_b32_e32 v42, v0
	v_mov_b32_e32 v43, v0
	v_mov_b32_e32 v44, v0
	v_mov_b32_e32 v45, v0
	v_mov_b32_e32 v46, v0
	v_mov_b32_e32 v47, v0
	v_mov_b32_e32 v48, v0
	v_mov_b32_e32 v49, v0
	v_mov_b32_e32 v50, v0
	v_mov_b32_e32 v51, v0
	v_mov_b32_e32 v52, v0
	v_mov_b32_e32 v53, v0
	v_mov_b32_e32 v54, v0
	v_mov_b32_e32 v55, v0
	v_mov_b32_e32 v56, v0
	v_mov_b32_e32 v57, v0
	v_mov_b32_e32 v58, v0
	v_mov_b32_e32 v59, v0
	v_mov_b32_e32 v60, v0
	v_mov_b32_e32 v61, v0
	v_mov_b32_e32 v62, v0
	v_mov_b32_e32 v63, v0
	v_mov_b32_e32 v104, v0
	v_mov_b32_e32 v105, v0
	v_mov_b32_e32 v106, v0
	v_mov_b32_e32 v107, v0
	v_mov_b32_e32 v108, v0
	v_mov_b32_e32 v109, v0
	v_mov_b32_e32 v110, v0
	v_mov_b32_e32 v111, v0
	v_mov_b32_e32 v112, v0
	v_mov_b32_e32 v113, v0
	v_mov_b32_e32 v114, v0
	v_mov_b32_e32 v115, v0
	v_mov_b32_e32 v116, v0
	v_mov_b32_e32 v117, v0
	v_mov_b32_e32 v118, v0
	v_mov_b32_e32 v119, v0
	v_mov_b32_e32 v120, v0
	v_mov_b32_e32 v121, v0
	v_mov_b32_e32 v122, v0
	v_mov_b32_e32 v123, v0
	v_mov_b32_e32 v124, v0
	v_mov_b32_e32 v125, v0
	v_mov_b32_e32 v126, v0
	v_mov_b32_e32 v127, v0
	v_mov_b32_e32 v132, v0
	v_mov_b32_e32 v133, v0
	v_mov_b32_e32 v134, v0
	v_mov_b32_e32 v135, v0
	v_mov_b32_e32 v128, v0
	v_mov_b32_e32 v129, v0
	v_mov_b32_e32 v130, v0
	v_mov_b32_e32 v131, v0
	v_readfirstlane_b32 s101, v211
	s_cmp_ge_u32 s101, 0x100
	s_cbranch_scc0 .Lprio_skip6
	s_setprio 1

; template <class Epi, class Sched, bool ALIGN_EPI = false, bool SP2 = false>
; __device__ __forceinline__ void gemm_phase(PG8_LAS unsigned char* lds, const Gemm g, const Sched& S, const Epi& E) {
;     ...
;         if (!has_next) break;
; #pragma unroll
;         for (int a = 0; a < 2; ++a)
; #pragma unroll
;             for (int b = 0; b < 2; ++b)
; #pragma unroll
;                 for (int m = 0; m < 4; ++m)
; #pragma unroll
;                     for (int n = 0; n < 2; ++n) acc[a][b][m][n] = (f32x4){0.f, 0.f, 0.f, 0.f};
;         cur = nxt; cA = nA; cB = nB; ++ui;
.LBB0_564:
	v_mov_b32_e32 v123, 0
	s_andn2_b64 vcc, exec, s[10:11]
	v_mov_b32_e32 v122, v123
	v_mov_b32_e32 v121, v123
	v_mov_b32_e32 v120, v123
	v_mov_b32_e32 v127, v123
	v_mov_b32_e32 v126, v123
	v_mov_b32_e32 v125, v123
	v_mov_b32_e32 v124, v123
	v_mov_b32_e32 v111, v123
	v_mov_b32_e32 v110, v123
	v_mov_b32_e32 v109, v123
	v_mov_b32_e32 v108, v123
	v_mov_b32_e32 v107, v123
	v_mov_b32_e32 v106, v123
	v_mov_b32_e32 v105, v123
	v_mov_b32_e32 v104, v123
	v_mov_b32_e32 v95, v123
	v_mov_b32_e32 v94, v123
	v_mov_b32_e32 v93, v123
	v_mov_b32_e32 v92, v123
	v_mov_b32_e32 v91, v123
	v_mov_b32_e32 v90, v123
	v_mov_b32_e32 v89, v123
	v_mov_b32_e32 v88, v123
	v_mov_b32_e32 v79, v123
	v_mov_b32_e32 v78, v123
	v_mov_b32_e32 v77, v123
	v_mov_b32_e32 v76, v123
	v_mov_b32_e32 v75, v123
	v_mov_b32_e32 v74, v123
	v_mov_b32_e32 v73, v123
	v_mov_b32_e32 v72, v123
	v_mov_b32_e32 v119, v123
	v_mov_b32_e32 v118, v123
	v_mov_b32_e32 v117, v123
	v_mov_b32_e32 v116, v123
	v_mov_b32_e32 v115, v123
	v_mov_b32_e32 v114, v123
	v_mov_b32_e32 v113, v123
	v_mov_b32_e32 v112, v123
	v_mov_b32_e32 v103, v123
	v_mov_b32_e32 v102, v123
	v_mov_b32_e32 v101, v123
	v_mov_b32_e32 v100, v123
	v_mov_b32_e32 v99, v123
	v_mov_b32_e32 v98, v123
	v_mov_b32_e32 v97, v123
	v_mov_b32_e32 v96, v123
	v_mov_b32_e32 v87, v123
	v_mov_b32_e32 v86, v123
	v_mov_b32_e32 v85, v123
	v_mov_b32_e32 v84, v123
	v_mov_b32_e32 v83, v123
	v_mov_b32_e32 v82, v123
	v_mov_b32_e32 v81, v123
	v_mov_b32_e32 v80, v123
	v_mov_b32_e32 v71, v123
	v_mov_b32_e32 v70, v123
	v_mov_b32_e32 v69, v123
	v_mov_b32_e32 v68, v123
	v_mov_b32_e32 v67, v123
	v_mov_b32_e32 v66, v123
	v_mov_b32_e32 v65, v123
	v_mov_b32_e32 v64, v123
	v_mov_b32_e32 v63, v123
	v_mov_b32_e32 v62, v123
	v_mov_b32_e32 v61, v123
	v_mov_b32_e32 v60, v123
	v_mov_b32_e32 v59, v123
	v_mov_b32_e32 v58, v123
	v_mov_b32_e32 v57, v123
	v_mov_b32_e32 v56, v123
	v_mov_b32_e32 v47, v123
	v_mov_b32_e32 v46, v123
	v_mov_b32_e32 v45, v123
	v_mov_b32_e32 v44, v123
	v_mov_b32_e32 v43, v123
	v_mov_b32_e32 v42, v123
	v_mov_b32_e32 v41, v123
	v_mov_b32_e32 v40, v123
	v_mov_b32_e32 v31, v123
	v_mov_b32_e32 v30, v123
	v_mov_b32_e32 v29, v123
	v_mov_b32_e32 v28, v123
	v_mov_b32_e32 v27, v123
	v_mov_b32_e32 v26, v123
	v_mov_b32_e32 v25, v123
	v_mov_b32_e32 v24, v123
	v_mov_b32_e32 v15, v123
	v_mov_b32_e32 v14, v123
	v_mov_b32_e32 v13, v123
	v_mov_b32_e32 v12, v123
	v_mov_b32_e32 v11, v123
	v_mov_b32_e32 v10, v123
	v_mov_b32_e32 v9, v123
	v_mov_b32_e32 v8, v123
	v_mov_b32_e32 v55, v123
	v_mov_b32_e32 v54, v123
	v_mov_b32_e32 v53, v123
	v_mov_b32_e32 v52, v123
	v_mov_b32_e32 v51, v123
	v_mov_b32_e32 v50, v123
	v_mov_b32_e32 v49, v123
	v_mov_b32_e32 v48, v123
	v_mov_b32_e32 v39, v123
	v_mov_b32_e32 v38, v123
	v_mov_b32_e32 v37, v123
	v_mov_b32_e32 v36, v123
	v_mov_b32_e32 v35, v123
	v_mov_b32_e32 v34, v123
	v_mov_b32_e32 v33, v123
	v_mov_b32_e32 v32, v123
	v_mov_b32_e32 v23, v123
	v_mov_b32_e32 v22, v123
	v_mov_b32_e32 v21, v123
	v_mov_b32_e32 v20, v123
	v_mov_b32_e32 v19, v123
	v_mov_b32_e32 v18, v123
	v_mov_b32_e32 v17, v123
	v_mov_b32_e32 v16, v123
	v_mov_b32_e32 v7, v123
	v_mov_b32_e32 v6, v123
	v_mov_b32_e32 v5, v123
	v_mov_b32_e32 v4, v123
	v_mov_b32_e32 v3, v123
	v_mov_b32_e32 v2, v123
	v_mov_b32_e32 v1, v123
	v_mov_b32_e32 v0, v123
	s_cbranch_vccnz .LBB0_567
	s_add_u32 s20, s20, 0x80
	s_addc_u32 s21, s21, 0
	s_add_u32 s42, s22, 0x100
	v_mov_b32_e32 v0, 0
	s_addc_u32 s43, s23, 0
	s_mov_b32 s22, 0
	v_mov_b32_e32 v1, v0
	v_mov_b32_e32 v2, v0
	v_mov_b32_e32 v3, v0
	v_mov_b32_e32 v4, v0
	v_mov_b32_e32 v5, v0
	v_mov_b32_e32 v6, v0
	v_mov_b32_e32 v7, v0
	v_mov_b32_e32 v16, v0
	v_mov_b32_e32 v17, v0
	v_mov_b32_e32 v18, v0
	v_mov_b32_e32 v19, v0
	v_mov_b32_e32 v20, v0
	v_mov_b32_e32 v21, v0
	v_mov_b32_e32 v22, v0
	v_mov_b32_e32 v23, v0
	v_mov_b32_e32 v32, v0
	v_mov_b32_e32 v33, v0
	v_mov_b32_e32 v34, v0
	v_mov_b32_e32 v35, v0
	v_mov_b32_e32 v36, v0
	v_mov_b32_e32 v37, v0
	v_mov_b32_e32 v38, v0
	v_mov_b32_e32 v39, v0
	v_mov_b32_e32 v48, v0
	v_mov_b32_e32 v49, v0
	v_mov_b32_e32 v50, v0
	v_mov_b32_e32 v51, v0
	v_mov_b32_e32 v52, v0
	v_mov_b32_e32 v53, v0
	v_mov_b32_e32 v54, v0
	v_mov_b32_e32 v55, v0
	v_mov_b32_e32 v8, v0
	v_mov_b32_e32 v9, v0
	v_mov_b32_e32 v10, v0
	v_mov_b32_e32 v11, v0
	v_mov_b32_e32 v12, v0
	v_mov_b32_e32 v13, v0
	v_mov_b32_e32 v14, v0
	v_mov_b32_e32 v15, v0
	v_mov_b32_e32 v24, v0
	v_mov_b32_e32 v25, v0
	v_mov_b32_e32 v26, v0
	v_mov_b32_e32 v27, v0
	v_mov_b32_e32 v28, v0
	v_mov_b32_e32 v29, v0
	v_mov_b32_e32 v30, v0
	v_mov_b32_e32 v31, v0
	v_mov_b32_e32 v40, v0
	v_mov_b32_e32 v41, v0
	v_mov_b32_e32 v42, v0
	v_mov_b32_e32 v43, v0
	v_mov_b32_e32 v44, v0
	v_mov_b32_e32 v45, v0
	v_mov_b32_e32 v46, v0
	v_mov_b32_e32 v47, v0
	v_mov_b32_e32 v56, v0
	v_mov_b32_e32 v57, v0
	v_mov_b32_e32 v58, v0
	v_mov_b32_e32 v59, v0
	v_mov_b32_e32 v60, v0
	v_mov_b32_e32 v61, v0
	v_mov_b32_e32 v62, v0
	v_mov_b32_e32 v63, v0
	v_mov_b32_e32 v64, v0
	v_mov_b32_e32 v65, v0
	v_mov_b32_e32 v66, v0
	v_mov_b32_e32 v67, v0
	v_mov_b32_e32 v68, v0
	v_mov_b32_e32 v69, v0
	v_mov_b32_e32 v70, v0
	v_mov_b32_e32 v71, v0
	v_mov_b32_e32 v80, v0
	v_mov_b32_e32 v81, v0
	v_mov_b32_e32 v82, v0
	v_mov_b32_e32 v83, v0
	v_mov_b32_e32 v84, v0
	v_mov_b32_e32 v85, v0
	v_mov_b32_e32 v86, v0
	v_mov_b32_e32 v87, v0
	v_mov_b32_e32 v96, v0
	v_mov_b32_e32 v97, v0
	v_mov_b32_e32 v98, v0
	v_mov_b32_e32 v99, v0
	v_mov_b32_e32 v100, v0
	v_mov_b32_e32 v101, v0
	v_mov_b32_e32 v102, v0
	v_mov_b32_e32 v103, v0
	v_mov_b32_e32 v112, v0
	v_mov_b32_e32 v113, v0
	v_mov_b32_e32 v114, v0
	v_mov_b32_e32 v115, v0
	v_mov_b32_e32 v116, v0
	v_mov_b32_e32 v117, v0
	v_mov_b32_e32 v118, v0
	v_mov_b32_e32 v119, v0
	v_mov_b32_e32 v72, v0
	v_mov_b32_e32 v73, v0
	v_mov_b32_e32 v74, v0
	v_mov_b32_e32 v75, v0
	v_mov_b32_e32 v76, v0
	v_mov_b32_e32 v77, v0
	v_mov_b32_e32 v78, v0
	v_mov_b32_e32 v79, v0
	v_mov_b32_e32 v88, v0
	v_mov_b32_e32 v89, v0
	v_mov_b32_e32 v90, v0
	v_mov_b32_e32 v91, v0
	v_mov_b32_e32 v92, v0
	v_mov_b32_e32 v93, v0
	v_mov_b32_e32 v94, v0
	v_mov_b32_e32 v95, v0
	v_mov_b32_e32 v104, v0
	v_mov_b32_e32 v105, v0
	v_mov_b32_e32 v106, v0
	v_mov_b32_e32 v107, v0
	v_mov_b32_e32 v108, v0
	v_mov_b32_e32 v109, v0
	v_mov_b32_e32 v110, v0
	v_mov_b32_e32 v111, v0
	v_mov_b32_e32 v124, v0
	v_mov_b32_e32 v125, v0
	v_mov_b32_e32 v126, v0
	v_mov_b32_e32 v127, v0
	v_mov_b32_e32 v120, v0
	v_mov_b32_e32 v121, v0
	v_mov_b32_e32 v122, v0
	v_mov_b32_e32 v123, v0
	v_readfirstlane_b32 s101, v211
	s_cmp_ge_u32 s101, 0x100
	s_cbranch_scc0 .Lprio_skip5
	s_setprio 1

; template <class Epi, class Sched, bool ALIGN_EPI = false, bool SP2 = false>
; __device__ __forceinline__ void gemm_phase(PG8_LAS unsigned char* lds, const Gemm g, const Sched& S, const Epi& E) {
;     ...
;         if (!has_next) break;
; #pragma unroll
;         for (int a = 0; a < 2; ++a)
; #pragma unroll
;             for (int b = 0; b < 2; ++b)
; #pragma unroll
;                 for (int m = 0; m < 4; ++m)
; #pragma unroll
;                     for (int n = 0; n < 2; ++n) acc[a][b][m][n] = (f32x4){0.f, 0.f, 0.f, 0.f};
;         cur = nxt; cA = nA; cB = nB; ++ui;
.LBB0_628:
	v_mov_b32_e32 v123, 0
	s_andn2_b64 vcc, exec, s[10:11]
	v_mov_b32_e32 v122, v123
	v_mov_b32_e32 v121, v123
	v_mov_b32_e32 v120, v123
	v_mov_b32_e32 v127, v123
	v_mov_b32_e32 v126, v123
	v_mov_b32_e32 v125, v123
	v_mov_b32_e32 v124, v123
	v_mov_b32_e32 v111, v123
	v_mov_b32_e32 v110, v123
	v_mov_b32_e32 v109, v123
	v_mov_b32_e32 v108, v123
	v_mov_b32_e32 v107, v123
	v_mov_b32_e32 v106, v123
	v_mov_b32_e32 v105, v123
	v_mov_b32_e32 v104, v123
	v_mov_b32_e32 v95, v123
	v_mov_b32_e32 v94, v123
	v_mov_b32_e32 v93, v123
	v_mov_b32_e32 v92, v123
	v_mov_b32_e32 v91, v123
	v_mov_b32_e32 v90, v123
	v_mov_b32_e32 v89, v123
	v_mov_b32_e32 v88, v123
	v_mov_b32_e32 v79, v123
	v_mov_b32_e32 v78, v123
	v_mov_b32_e32 v77, v123
	v_mov_b32_e32 v76, v123
	v_mov_b32_e32 v75, v123
	v_mov_b32_e32 v74, v123
	v_mov_b32_e32 v73, v123
	v_mov_b32_e32 v72, v123
	v_mov_b32_e32 v119, v123
	v_mov_b32_e32 v118, v123
	v_mov_b32_e32 v117, v123
	v_mov_b32_e32 v116, v123
	v_mov_b32_e32 v115, v123
	v_mov_b32_e32 v114, v123
	v_mov_b32_e32 v113, v123
	v_mov_b32_e32 v112, v123
	v_mov_b32_e32 v103, v123
	v_mov_b32_e32 v102, v123
	v_mov_b32_e32 v101, v123
	v_mov_b32_e32 v100, v123
	v_mov_b32_e32 v99, v123
	v_mov_b32_e32 v98, v123
	v_mov_b32_e32 v97, v123
	v_mov_b32_e32 v96, v123
	v_mov_b32_e32 v87, v123
	v_mov_b32_e32 v86, v123
	v_mov_b32_e32 v85, v123
	v_mov_b32_e32 v84, v123
	v_mov_b32_e32 v83, v123
	v_mov_b32_e32 v82, v123
	v_mov_b32_e32 v81, v123
	v_mov_b32_e32 v80, v123
	v_mov_b32_e32 v71, v123
	v_mov_b32_e32 v70, v123
	v_mov_b32_e32 v69, v123
	v_mov_b32_e32 v68, v123
	v_mov_b32_e32 v67, v123
	v_mov_b32_e32 v66, v123
	v_mov_b32_e32 v65, v123
	v_mov_b32_e32 v64, v123
	v_mov_b32_e32 v63, v123
	v_mov_b32_e32 v62, v123
	v_mov_b32_e32 v61, v123
	v_mov_b32_e32 v60, v123
	v_mov_b32_e32 v59, v123
	v_mov_b32_e32 v58, v123
	v_mov_b32_e32 v57, v123
	v_mov_b32_e32 v56, v123
	v_mov_b32_e32 v47, v123
	v_mov_b32_e32 v46, v123
	v_mov_b32_e32 v45, v123
	v_mov_b32_e32 v44, v123
	v_mov_b32_e32 v43, v123
	v_mov_b32_e32 v42, v123
	v_mov_b32_e32 v41, v123
	v_mov_b32_e32 v40, v123
	v_mov_b32_e32 v31, v123
	v_mov_b32_e32 v30, v123
	v_mov_b32_e32 v29, v123
	v_mov_b32_e32 v28, v123
	v_mov_b32_e32 v27, v123
	v_mov_b32_e32 v26, v123
	v_mov_b32_e32 v25, v123
	v_mov_b32_e32 v24, v123
	v_mov_b32_e32 v15, v123
	v_mov_b32_e32 v14, v123
	v_mov_b32_e32 v13, v123
	v_mov_b32_e32 v12, v123
	v_mov_b32_e32 v11, v123
	v_mov_b32_e32 v10, v123
	v_mov_b32_e32 v9, v123
	v_mov_b32_e32 v8, v123
	v_mov_b32_e32 v55, v123
	v_mov_b32_e32 v54, v123
	v_mov_b32_e32 v53, v123
	v_mov_b32_e32 v52, v123
	v_mov_b32_e32 v51, v123
	v_mov_b32_e32 v50, v123
	v_mov_b32_e32 v49, v123
	v_mov_b32_e32 v48, v123
	v_mov_b32_e32 v39, v123
	v_mov_b32_e32 v38, v123
	v_mov_b32_e32 v37, v123
	v_mov_b32_e32 v36, v123
	v_mov_b32_e32 v35, v123
	v_mov_b32_e32 v34, v123
	v_mov_b32_e32 v33, v123
	v_mov_b32_e32 v32, v123
	v_mov_b32_e32 v23, v123
	v_mov_b32_e32 v22, v123
	v_mov_b32_e32 v21, v123
	v_mov_b32_e32 v20, v123
	v_mov_b32_e32 v19, v123
	v_mov_b32_e32 v18, v123
	v_mov_b32_e32 v17, v123
	v_mov_b32_e32 v16, v123
	v_mov_b32_e32 v7, v123
	v_mov_b32_e32 v6, v123
	v_mov_b32_e32 v5, v123
	v_mov_b32_e32 v4, v123
	v_mov_b32_e32 v3, v123
	v_mov_b32_e32 v2, v123
	v_mov_b32_e32 v1, v123
	v_mov_b32_e32 v0, v123
	s_cbranch_vccnz .LBB0_631
	s_add_u32 s6, s20, 0x80
	s_addc_u32 s7, s21, 0
	s_add_u32 s20, s18, 0x100
	v_mov_b32_e32 v0, 0
	s_addc_u32 s21, s19, 0
	s_mov_b32 s18, 0
	v_mov_b32_e32 v1, v0
	v_mov_b32_e32 v2, v0
	v_mov_b32_e32 v3, v0
	v_mov_b32_e32 v4, v0
	v_mov_b32_e32 v5, v0
	v_mov_b32_e32 v6, v0
	v_mov_b32_e32 v7, v0
	v_mov_b32_e32 v16, v0
	v_mov_b32_e32 v17, v0
	v_mov_b32_e32 v18, v0
	v_mov_b32_e32 v19, v0
	v_mov_b32_e32 v20, v0
	v_mov_b32_e32 v21, v0
	v_mov_b32_e32 v22, v0
	v_mov_b32_e32 v23, v0
	v_mov_b32_e32 v32, v0
	v_mov_b32_e32 v33, v0
	v_mov_b32_e32 v34, v0
	v_mov_b32_e32 v35, v0
	v_mov_b32_e32 v36, v0
	v_mov_b32_e32 v37, v0
	v_mov_b32_e32 v38, v0
	v_mov_b32_e32 v39, v0
	v_mov_b32_e32 v48, v0
	v_mov_b32_e32 v49, v0
	v_mov_b32_e32 v50, v0
	v_mov_b32_e32 v51, v0
	v_mov_b32_e32 v52, v0
	v_mov_b32_e32 v53, v0
	v_mov_b32_e32 v54, v0
	v_mov_b32_e32 v55, v0
	v_mov_b32_e32 v8, v0
	v_mov_b32_e32 v9, v0
	v_mov_b32_e32 v10, v0
	v_mov_b32_e32 v11, v0
	v_mov_b32_e32 v12, v0
	v_mov_b32_e32 v13, v0
	v_mov_b32_e32 v14, v0
	v_mov_b32_e32 v15, v0
	v_mov_b32_e32 v24, v0
	v_mov_b32_e32 v25, v0
	v_mov_b32_e32 v26, v0
	v_mov_b32_e32 v27, v0
	v_mov_b32_e32 v28, v0
	v_mov_b32_e32 v29, v0
	v_mov_b32_e32 v30, v0
	v_mov_b32_e32 v31, v0
	v_mov_b32_e32 v40, v0
	v_mov_b32_e32 v41, v0
	v_mov_b32_e32 v42, v0
	v_mov_b32_e32 v43, v0
	v_mov_b32_e32 v44, v0
	v_mov_b32_e32 v45, v0
	v_mov_b32_e32 v46, v0
	v_mov_b32_e32 v47, v0
	v_mov_b32_e32 v56, v0
	v_mov_b32_e32 v57, v0
	v_mov_b32_e32 v58, v0
	v_mov_b32_e32 v59, v0
	v_mov_b32_e32 v60, v0
	v_mov_b32_e32 v61, v0
	v_mov_b32_e32 v62, v0
	v_mov_b32_e32 v63, v0
	v_mov_b32_e32 v64, v0
	v_mov_b32_e32 v65, v0
	v_mov_b32_e32 v66, v0
	v_mov_b32_e32 v67, v0
	v_mov_b32_e32 v68, v0
	v_mov_b32_e32 v69, v0
	v_mov_b32_e32 v70, v0
	v_mov_b32_e32 v71, v0
	v_mov_b32_e32 v80, v0
	v_mov_b32_e32 v81, v0
	v_mov_b32_e32 v82, v0
	v_mov_b32_e32 v83, v0
	v_mov_b32_e32 v84, v0
	v_mov_b32_e32 v85, v0
	v_mov_b32_e32 v86, v0
	v_mov_b32_e32 v87, v0
	v_mov_b32_e32 v96, v0
	v_mov_b32_e32 v97, v0
	v_mov_b32_e32 v98, v0
	v_mov_b32_e32 v99, v0
	v_mov_b32_e32 v100, v0
	v_mov_b32_e32 v101, v0
	v_mov_b32_e32 v102, v0
	v_mov_b32_e32 v103, v0
	v_mov_b32_e32 v112, v0
	v_mov_b32_e32 v113, v0
	v_mov_b32_e32 v114, v0
	v_mov_b32_e32 v115, v0
	v_mov_b32_e32 v116, v0
	v_mov_b32_e32 v117, v0
	v_mov_b32_e32 v118, v0
	v_mov_b32_e32 v119, v0
	v_mov_b32_e32 v72, v0
	v_mov_b32_e32 v73, v0
	v_mov_b32_e32 v74, v0
	v_mov_b32_e32 v75, v0
	v_mov_b32_e32 v76, v0
	v_mov_b32_e32 v77, v0
	v_mov_b32_e32 v78, v0
	v_mov_b32_e32 v79, v0
	v_mov_b32_e32 v88, v0
	v_mov_b32_e32 v89, v0
	v_mov_b32_e32 v90, v0
	v_mov_b32_e32 v91, v0
	v_mov_b32_e32 v92, v0
	v_mov_b32_e32 v93, v0
	v_mov_b32_e32 v94, v0
	v_mov_b32_e32 v95, v0
	v_mov_b32_e32 v104, v0
	v_mov_b32_e32 v105, v0
	v_mov_b32_e32 v106, v0
	v_mov_b32_e32 v107, v0
	v_mov_b32_e32 v108, v0
	v_mov_b32_e32 v109, v0
	v_mov_b32_e32 v110, v0
	v_mov_b32_e32 v111, v0
	v_mov_b32_e32 v124, v0
	v_mov_b32_e32 v125, v0
	v_mov_b32_e32 v126, v0
	v_mov_b32_e32 v127, v0
	v_mov_b32_e32 v120, v0
	v_mov_b32_e32 v121, v0
	v_mov_b32_e32 v122, v0
	v_mov_b32_e32 v123, v0
	v_readfirstlane_b32 s101, v211
	s_cmp_ge_u32 s101, 0x100
	s_cbranch_scc0 .Lprio_skip4
	s_setprio 1

; template <class Epi, class Sched, bool ALIGN_EPI = false, bool SP2 = false>
; __device__ __forceinline__ void gemm_phase(PG8_LAS unsigned char* lds, const Gemm g, const Sched& S, const Epi& E) {
;     ...
;         if (!has_next) break;
; #pragma unroll
;         for (int a = 0; a < 2; ++a)
; #pragma unroll
;             for (int b = 0; b < 2; ++b)
; #pragma unroll
;                 for (int m = 0; m < 4; ++m)
; #pragma unroll
;                     for (int n = 0; n < 2; ++n) acc[a][b][m][n] = (f32x4){0.f, 0.f, 0.f, 0.f};
;         cur = nxt; cA = nA; cB = nB; ++ui;
.LBB0_811:
	v_mov_b32_e32 v135, 0
	s_andn2_b64 vcc, exec, s[18:19]
	v_mov_b32_e32 v134, 0
	v_mov_b32_e32 v137, 0
	v_mov_b32_e32 v136, 0
	v_mov_b32_e32 v127, 0
	v_mov_b32_e32 v126, 0
	v_mov_b32_e32 v125, 0
	v_mov_b32_e32 v124, 0
	v_mov_b32_e32 v119, 0
	v_mov_b32_e32 v118, 0
	v_mov_b32_e32 v117, 0
	v_mov_b32_e32 v116, 0
	v_mov_b32_e32 v111, 0
	v_mov_b32_e32 v110, 0
	v_mov_b32_e32 v109, 0
	v_mov_b32_e32 v108, 0
	v_mov_b32_e32 v103, 0
	v_mov_b32_e32 v102, 0
	v_mov_b32_e32 v101, 0
	v_mov_b32_e32 v100, 0
	v_mov_b32_e32 v95, 0
	v_mov_b32_e32 v94, 0
	v_mov_b32_e32 v93, 0
	v_mov_b32_e32 v92, 0
	v_mov_b32_e32 v87, 0
	v_mov_b32_e32 v86, 0
	v_mov_b32_e32 v85, 0
	v_mov_b32_e32 v84, 0
	v_mov_b32_e32 v75, 0
	v_mov_b32_e32 v74, 0
	v_mov_b32_e32 v73, 0
	v_mov_b32_e32 v72, 0
	v_mov_b32_e32 v145, 0
	v_mov_b32_e32 v144, 0
	v_mov_b32_e32 v143, 0
	v_mov_b32_e32 v142, 0
	v_mov_b32_e32 v141, 0
	v_mov_b32_e32 v140, 0
	v_mov_b32_e32 v139, 0
	v_mov_b32_e32 v138, 0
	v_mov_b32_e32 v123, 0
	v_mov_b32_e32 v122, 0
	v_mov_b32_e32 v121, 0
	v_mov_b32_e32 v120, 0
	v_mov_b32_e32 v115, 0
	v_mov_b32_e32 v114, 0
	v_mov_b32_e32 v113, 0
	v_mov_b32_e32 v112, 0
	v_mov_b32_e32 v107, 0
	v_mov_b32_e32 v106, 0
	v_mov_b32_e32 v105, 0
	v_mov_b32_e32 v104, 0
	v_mov_b32_e32 v99, 0
	v_mov_b32_e32 v98, 0
	v_mov_b32_e32 v97, 0
	v_mov_b32_e32 v96, 0
	v_mov_b32_e32 v91, 0
	v_mov_b32_e32 v90, 0
	v_mov_b32_e32 v89, 0
	v_mov_b32_e32 v88, 0
	v_mov_b32_e32 v83, 0
	v_mov_b32_e32 v82, 0
	v_mov_b32_e32 v81, 0
	v_mov_b32_e32 v80, 0
	v_mov_b32_e32 v67, 0
	v_mov_b32_e32 v66, 0
	v_mov_b32_e32 v65, 0
	v_mov_b32_e32 v64, 0
	v_mov_b32_e32 v63, 0
	v_mov_b32_e32 v62, 0
	v_mov_b32_e32 v61, 0
	v_mov_b32_e32 v60, 0
	v_mov_b32_e32 v55, 0
	v_mov_b32_e32 v54, 0
	v_mov_b32_e32 v53, 0
	v_mov_b32_e32 v52, 0
	v_mov_b32_e32 v47, 0
	v_mov_b32_e32 v46, 0
	v_mov_b32_e32 v45, 0
	v_mov_b32_e32 v44, 0
	v_mov_b32_e32 v31, 0
	v_mov_b32_e32 v30, 0
	v_mov_b32_e32 v29, 0
	v_mov_b32_e32 v28, 0
	v_mov_b32_e32 v23, 0
	v_mov_b32_e32 v22, 0
	v_mov_b32_e32 v21, 0
	v_mov_b32_e32 v20, 0
	v_mov_b32_e32 v15, 0
	v_mov_b32_e32 v14, 0
	v_mov_b32_e32 v13, 0
	v_mov_b32_e32 v12, 0
	v_mov_b32_e32 v11, 0
	v_mov_b32_e32 v10, 0
	v_mov_b32_e32 v9, 0
	v_mov_b32_e32 v8, 0
	v_mov_b32_e32 v79, 0
	v_mov_b32_e32 v78, 0
	v_mov_b32_e32 v77, 0
	v_mov_b32_e32 v76, 0
	v_mov_b32_e32 v71, 0
	v_mov_b32_e32 v70, 0
	v_mov_b32_e32 v69, 0
	v_mov_b32_e32 v68, 0
	v_mov_b32_e32 v59, 0
	v_mov_b32_e32 v58, 0
	v_mov_b32_e32 v57, 0
	v_mov_b32_e32 v56, 0
	v_mov_b32_e32 v51, 0
	v_mov_b32_e32 v50, 0
	v_mov_b32_e32 v49, 0
	v_mov_b32_e32 v48, 0
	v_mov_b32_e32 v39, 0
	v_mov_b32_e32 v38, 0
	v_mov_b32_e32 v37, 0
	v_mov_b32_e32 v36, 0
	v_mov_b32_e32 v35, 0
	v_mov_b32_e32 v34, 0
	v_mov_b32_e32 v33, 0
	v_mov_b32_e32 v32, 0
	v_mov_b32_e32 v7, 0
	v_mov_b32_e32 v6, 0
	v_mov_b32_e32 v5, 0
	v_mov_b32_e32 v4, 0
	v_mov_b32_e32 v3, 0
	v_mov_b32_e32 v2, 0
	v_mov_b32_e32 v1, 0
	v_mov_b32_e32 v0, 0
	s_cbranch_vccnz .LBB0_815
	s_add_u32 s0, s0, 0x80
	s_addc_u32 s1, s1, 0
	s_add_u32 s36, s2, 0x100
	v_mov_b32_e32 v0, 0
	s_addc_u32 s37, s3, 0
	s_mov_b32 s2, 0
	v_mov_b32_e32 v1, v0
	v_mov_b32_e32 v2, v0
	v_mov_b32_e32 v3, v0
	v_mov_b32_e32 v4, v0
	v_mov_b32_e32 v5, v0
	v_mov_b32_e32 v6, v0
	v_mov_b32_e32 v7, v0
	v_mov_b32_e32 v8, v0
	v_mov_b32_e32 v9, v0
	v_mov_b32_e32 v10, v0
	v_mov_b32_e32 v11, v0
	v_mov_b32_e32 v12, v0
	v_mov_b32_e32 v13, v0
	v_mov_b32_e32 v14, v0
	v_mov_b32_e32 v15, v0
	v_mov_b32_e32 v20, v0
	v_mov_b32_e32 v21, v0
	v_mov_b32_e32 v22, v0
	v_mov_b32_e32 v23, v0
	v_mov_b32_e32 v28, v0
	v_mov_b32_e32 v29, v0
	v_mov_b32_e32 v30, v0
	v_mov_b32_e32 v31, v0
	v_mov_b32_e32 v36, v0
	v_mov_b32_e32 v37, v0
	v_mov_b32_e32 v38, v0
	v_mov_b32_e32 v39, v0
	v_mov_b32_e32 v44, v0
	v_mov_b32_e32 v45, v0
	v_mov_b32_e32 v46, v0
	v_mov_b32_e32 v47, v0
	v_mov_b32_e32 v16, v0
	v_mov_b32_e32 v17, v0
	v_mov_b32_e32 v18, v0
	v_mov_b32_e32 v19, v0
	v_mov_b32_e32 v24, v0
	v_mov_b32_e32 v25, v0
	v_mov_b32_e32 v26, v0
	v_mov_b32_e32 v27, v0
	v_mov_b32_e32 v32, v0
	v_mov_b32_e32 v33, v0
	v_mov_b32_e32 v34, v0
	v_mov_b32_e32 v35, v0
	v_mov_b32_e32 v40, v0
	v_mov_b32_e32 v41, v0
	v_mov_b32_e32 v42, v0
	v_mov_b32_e32 v43, v0
	v_mov_b32_e32 v48, v0
	v_mov_b32_e32 v49, v0
	v_mov_b32_e32 v50, v0
	v_mov_b32_e32 v51, v0
	v_mov_b32_e32 v52, v0
	v_mov_b32_e32 v53, v0
	v_mov_b32_e32 v54, v0
	v_mov_b32_e32 v55, v0
	v_mov_b32_e32 v56, v0
	v_mov_b32_e32 v57, v0
	v_mov_b32_e32 v58, v0
	v_mov_b32_e32 v59, v0
	v_mov_b32_e32 v60, v0
	v_mov_b32_e32 v61, v0
	v_mov_b32_e32 v62, v0
	v_mov_b32_e32 v63, v0
	v_mov_b32_e32 v64, v0
	v_mov_b32_e32 v65, v0
	v_mov_b32_e32 v66, v0
	v_mov_b32_e32 v67, v0
	v_mov_b32_e32 v68, v0
	v_mov_b32_e32 v69, v0
	v_mov_b32_e32 v70, v0
	v_mov_b32_e32 v71, v0
	v_mov_b32_e32 v72, v0
	v_mov_b32_e32 v73, v0
	v_mov_b32_e32 v74, v0
	v_mov_b32_e32 v75, v0
	v_mov_b32_e32 v76, v0
	v_mov_b32_e32 v77, v0
	v_mov_b32_e32 v78, v0
	v_mov_b32_e32 v79, v0
	v_mov_b32_e32 v84, v0
	v_mov_b32_e32 v85, v0
	v_mov_b32_e32 v86, v0
	v_mov_b32_e32 v87, v0
	v_mov_b32_e32 v92, v0
	v_mov_b32_e32 v93, v0
	v_mov_b32_e32 v94, v0
	v_mov_b32_e32 v95, v0
	v_mov_b32_e32 v100, v0
	v_mov_b32_e32 v101, v0
	v_mov_b32_e32 v102, v0
	v_mov_b32_e32 v103, v0
	v_mov_b32_e32 v108, v0
	v_mov_b32_e32 v109, v0
	v_mov_b32_e32 v110, v0
	v_mov_b32_e32 v111, v0
	v_mov_b32_e32 v80, v0
	v_mov_b32_e32 v81, v0
	v_mov_b32_e32 v82, v0
	v_mov_b32_e32 v83, v0
	v_mov_b32_e32 v88, v0
	v_mov_b32_e32 v89, v0
	v_mov_b32_e32 v90, v0
	v_mov_b32_e32 v91, v0
	v_mov_b32_e32 v96, v0
	v_mov_b32_e32 v97, v0
	v_mov_b32_e32 v98, v0
	v_mov_b32_e32 v99, v0
	v_mov_b32_e32 v104, v0
	v_mov_b32_e32 v105, v0
	v_mov_b32_e32 v106, v0
	v_mov_b32_e32 v107, v0
	v_mov_b32_e32 v112, v0
	v_mov_b32_e32 v113, v0
	v_mov_b32_e32 v114, v0
	v_mov_b32_e32 v115, v0
	v_mov_b32_e32 v116, v0
	v_mov_b32_e32 v117, v0
	v_mov_b32_e32 v118, v0
	v_mov_b32_e32 v119, v0
	v_mov_b32_e32 v120, v0
	v_mov_b32_e32 v121, v0
	v_mov_b32_e32 v122, v0
	v_mov_b32_e32 v123, v0
	v_mov_b32_e32 v124, v0
	v_mov_b32_e32 v125, v0
	v_mov_b32_e32 v126, v0
	v_mov_b32_e32 v127, v0
	v_readfirstlane_b32 s101, v211
	s_cmp_ge_u32 s101, 0x100
	s_cbranch_scc0 .Lprio_skip2
	s_setprio 1

; template <class Epi, class Sched, bool ALIGN_EPI = false, bool SP2 = false>
; __device__ __forceinline__ void gemm_phase(PG8_LAS unsigned char* lds, const Gemm g, const Sched& S, const Epi& E) {
;     ...
;         if (!has_next) break;
; #pragma unroll
;         for (int a = 0; a < 2; ++a)
; #pragma unroll
;             for (int b = 0; b < 2; ++b)
; #pragma unroll
;                 for (int m = 0; m < 4; ++m)
; #pragma unroll
;                     for (int n = 0; n < 2; ++n) acc[a][b][m][n] = (f32x4){0.f, 0.f, 0.f, 0.f};
;         cur = nxt; cA = nA; cB = nB; ++ui;
.LBB0_838:
	v_mov_b32_e32 v123, 0
	s_andn2_b64 vcc, exec, s[18:19]
	v_mov_b32_e32 v122, v123
	v_mov_b32_e32 v121, v123
	v_mov_b32_e32 v120, v123
	v_mov_b32_e32 v115, v123
	v_mov_b32_e32 v114, v123
	v_mov_b32_e32 v113, v123
	v_mov_b32_e32 v112, v123
	v_mov_b32_e32 v107, v123
	v_mov_b32_e32 v106, v123
	v_mov_b32_e32 v105, v123
	v_mov_b32_e32 v104, v123
	v_mov_b32_e32 v99, v123
	v_mov_b32_e32 v98, v123
	v_mov_b32_e32 v97, v123
	v_mov_b32_e32 v96, v123
	v_mov_b32_e32 v91, v123
	v_mov_b32_e32 v90, v123
	v_mov_b32_e32 v89, v123
	v_mov_b32_e32 v88, v123
	v_mov_b32_e32 v83, v123
	v_mov_b32_e32 v82, v123
	v_mov_b32_e32 v81, v123
	v_mov_b32_e32 v80, v123
	v_mov_b32_e32 v75, v123
	v_mov_b32_e32 v74, v123
	v_mov_b32_e32 v73, v123
	v_mov_b32_e32 v72, v123
	v_mov_b32_e32 v67, v123
	v_mov_b32_e32 v66, v123
	v_mov_b32_e32 v65, v123
	v_mov_b32_e32 v64, v123
	v_mov_b32_e32 v127, v123
	v_mov_b32_e32 v126, v123
	v_mov_b32_e32 v125, v123
	v_mov_b32_e32 v124, v123
	v_mov_b32_e32 v119, v123
	v_mov_b32_e32 v118, v123
	v_mov_b32_e32 v117, v123
	v_mov_b32_e32 v116, v123
	v_mov_b32_e32 v111, v123
	v_mov_b32_e32 v110, v123
	v_mov_b32_e32 v109, v123
	v_mov_b32_e32 v108, v123
	v_mov_b32_e32 v103, v123
	v_mov_b32_e32 v102, v123
	v_mov_b32_e32 v101, v123
	v_mov_b32_e32 v100, v123
	v_mov_b32_e32 v95, v123
	v_mov_b32_e32 v94, v123
	v_mov_b32_e32 v93, v123
	v_mov_b32_e32 v92, v123
	v_mov_b32_e32 v87, v123
	v_mov_b32_e32 v86, v123
	v_mov_b32_e32 v85, v123
	v_mov_b32_e32 v84, v123
	v_mov_b32_e32 v79, v123
	v_mov_b32_e32 v78, v123
	v_mov_b32_e32 v77, v123
	v_mov_b32_e32 v76, v123
	v_mov_b32_e32 v71, v123
	v_mov_b32_e32 v70, v123
	v_mov_b32_e32 v69, v123
	v_mov_b32_e32 v68, v123
	v_mov_b32_e32 v59, v123
	v_mov_b32_e32 v58, v123
	v_mov_b32_e32 v57, v123
	v_mov_b32_e32 v56, v123
	v_mov_b32_e32 v51, v123
	v_mov_b32_e32 v50, v123
	v_mov_b32_e32 v49, v123
	v_mov_b32_e32 v48, v123
	v_mov_b32_e32 v43, v123
	v_mov_b32_e32 v42, v123
	v_mov_b32_e32 v41, v123
	v_mov_b32_e32 v40, v123
	v_mov_b32_e32 v35, v123
	v_mov_b32_e32 v34, v123
	v_mov_b32_e32 v33, v123
	v_mov_b32_e32 v32, v123
	v_mov_b32_e32 v27, v123
	v_mov_b32_e32 v26, v123
	v_mov_b32_e32 v25, v123
	v_mov_b32_e32 v24, v123
	v_mov_b32_e32 v19, v123
	v_mov_b32_e32 v18, v123
	v_mov_b32_e32 v17, v123
	v_mov_b32_e32 v16, v123
	v_mov_b32_e32 v11, v123
	v_mov_b32_e32 v10, v123
	v_mov_b32_e32 v9, v123
	v_mov_b32_e32 v8, v123
	v_mov_b32_e32 v3, v123
	v_mov_b32_e32 v2, v123
	v_mov_b32_e32 v1, v123
	v_mov_b32_e32 v0, v123
	v_mov_b32_e32 v63, v123
	v_mov_b32_e32 v62, v123
	v_mov_b32_e32 v61, v123
	v_mov_b32_e32 v60, v123
	v_mov_b32_e32 v55, v123
	v_mov_b32_e32 v54, v123
	v_mov_b32_e32 v53, v123
	v_mov_b32_e32 v52, v123
	v_mov_b32_e32 v47, v123
	v_mov_b32_e32 v46, v123
	v_mov_b32_e32 v45, v123
	v_mov_b32_e32 v44, v123
	v_mov_b32_e32 v39, v123
	v_mov_b32_e32 v38, v123
	v_mov_b32_e32 v37, v123
	v_mov_b32_e32 v36, v123
	v_mov_b32_e32 v31, v123
	v_mov_b32_e32 v30, v123
	v_mov_b32_e32 v29, v123
	v_mov_b32_e32 v28, v123
	v_mov_b32_e32 v23, v123
	v_mov_b32_e32 v22, v123
	v_mov_b32_e32 v21, v123
	v_mov_b32_e32 v20, v123
	v_mov_b32_e32 v15, v123
	v_mov_b32_e32 v14, v123
	v_mov_b32_e32 v13, v123
	v_mov_b32_e32 v12, v123
	v_mov_b32_e32 v7, v123
	v_mov_b32_e32 v6, v123
	v_mov_b32_e32 v5, v123
	v_mov_b32_e32 v4, v123
	s_cbranch_vccnz .LBB0_841
	s_add_u32 s0, s0, 0x80
	s_addc_u32 s1, s1, 0
	s_add_u32 s36, s2, 0x100
	v_mov_b32_e32 v4, 0
	s_addc_u32 s37, s3, 0
	s_mov_b32 s2, 0
	v_mov_b32_e32 v5, v4
	v_mov_b32_e32 v6, v4
	v_mov_b32_e32 v7, v4
	v_mov_b32_e32 v12, v4
	v_mov_b32_e32 v13, v4
	v_mov_b32_e32 v14, v4
	v_mov_b32_e32 v15, v4
	v_mov_b32_e32 v20, v4
	v_mov_b32_e32 v21, v4
	v_mov_b32_e32 v22, v4
	v_mov_b32_e32 v23, v4
	v_mov_b32_e32 v28, v4
	v_mov_b32_e32 v29, v4
	v_mov_b32_e32 v30, v4
	v_mov_b32_e32 v31, v4
	v_mov_b32_e32 v36, v4
	v_mov_b32_e32 v37, v4
	v_mov_b32_e32 v38, v4
	v_mov_b32_e32 v39, v4
	v_mov_b32_e32 v44, v4
	v_mov_b32_e32 v45, v4
	v_mov_b32_e32 v46, v4
	v_mov_b32_e32 v47, v4
	v_mov_b32_e32 v52, v4
	v_mov_b32_e32 v53, v4
	v_mov_b32_e32 v54, v4
	v_mov_b32_e32 v55, v4
	v_mov_b32_e32 v60, v4
	v_mov_b32_e32 v61, v4
	v_mov_b32_e32 v62, v4
	v_mov_b32_e32 v63, v4
	v_mov_b32_e32 v0, v4
	v_mov_b32_e32 v1, v4
	v_mov_b32_e32 v2, v4
	v_mov_b32_e32 v3, v4
	v_mov_b32_e32 v8, v4
	v_mov_b32_e32 v9, v4
	v_mov_b32_e32 v10, v4
	v_mov_b32_e32 v11, v4
	v_mov_b32_e32 v16, v4
	v_mov_b32_e32 v17, v4
	v_mov_b32_e32 v18, v4
	v_mov_b32_e32 v19, v4
	v_mov_b32_e32 v24, v4
	v_mov_b32_e32 v25, v4
	v_mov_b32_e32 v26, v4
	v_mov_b32_e32 v27, v4
	v_mov_b32_e32 v32, v4
	v_mov_b32_e32 v33, v4
	v_mov_b32_e32 v34, v4
	v_mov_b32_e32 v35, v4
	v_mov_b32_e32 v40, v4
	v_mov_b32_e32 v41, v4
	v_mov_b32_e32 v42, v4
	v_mov_b32_e32 v43, v4
	v_mov_b32_e32 v48, v4
	v_mov_b32_e32 v49, v4
	v_mov_b32_e32 v50, v4
	v_mov_b32_e32 v51, v4
	v_mov_b32_e32 v56, v4
	v_mov_b32_e32 v57, v4
	v_mov_b32_e32 v58, v4
	v_mov_b32_e32 v59, v4
	v_mov_b32_e32 v68, v4
	v_mov_b32_e32 v69, v4
	v_mov_b32_e32 v70, v4
	v_mov_b32_e32 v71, v4
	v_mov_b32_e32 v76, v4
	v_mov_b32_e32 v77, v4
	v_mov_b32_e32 v78, v4
	v_mov_b32_e32 v79, v4
	v_mov_b32_e32 v84, v4
	v_mov_b32_e32 v85, v4
	v_mov_b32_e32 v86, v4
	v_mov_b32_e32 v87, v4
	v_mov_b32_e32 v92, v4
	v_mov_b32_e32 v93, v4
	v_mov_b32_e32 v94, v4
	v_mov_b32_e32 v95, v4
	v_mov_b32_e32 v100, v4
	v_mov_b32_e32 v101, v4
	v_mov_b32_e32 v102, v4
	v_mov_b32_e32 v103, v4
	v_mov_b32_e32 v108, v4
	v_mov_b32_e32 v109, v4
	v_mov_b32_e32 v110, v4
	v_mov_b32_e32 v111, v4
	v_mov_b32_e32 v116, v4
	v_mov_b32_e32 v117, v4
	v_mov_b32_e32 v118, v4
	v_mov_b32_e32 v119, v4
	v_mov_b32_e32 v124, v4
	v_mov_b32_e32 v125, v4
	v_mov_b32_e32 v126, v4
	v_mov_b32_e32 v127, v4
	v_mov_b32_e32 v64, v4
	v_mov_b32_e32 v65, v4
	v_mov_b32_e32 v66, v4
	v_mov_b32_e32 v67, v4
	v_mov_b32_e32 v72, v4
	v_mov_b32_e32 v73, v4
	v_mov_b32_e32 v74, v4
	v_mov_b32_e32 v75, v4
	v_mov_b32_e32 v80, v4
	v_mov_b32_e32 v81, v4
	v_mov_b32_e32 v82, v4
	v_mov_b32_e32 v83, v4
	v_mov_b32_e32 v88, v4
	v_mov_b32_e32 v89, v4
	v_mov_b32_e32 v90, v4
	v_mov_b32_e32 v91, v4
	v_mov_b32_e32 v96, v4
	v_mov_b32_e32 v97, v4
	v_mov_b32_e32 v98, v4
	v_mov_b32_e32 v99, v4
	v_mov_b32_e32 v104, v4
	v_mov_b32_e32 v105, v4
	v_mov_b32_e32 v106, v4
	v_mov_b32_e32 v107, v4
	v_mov_b32_e32 v112, v4
	v_mov_b32_e32 v113, v4
	v_mov_b32_e32 v114, v4
	v_mov_b32_e32 v115, v4
	v_mov_b32_e32 v120, v4
	v_mov_b32_e32 v121, v4
	v_mov_b32_e32 v122, v4
	v_mov_b32_e32 v123, v4
	v_readfirstlane_b32 s101, v211
	s_cmp_ge_u32 s101, 0x100
	s_cbranch_scc0 .Lprio_skip1
	s_setprio 1
